# bias folded into accumulator init for MLP1A/B, GIN, QKV q/k tiles (epilogue load-wait-add chains removed)
# speedup vs baseline: 1.0174x; 1.0028x over previous
.LBB0_448:
	s_and_b64 vcc, exec, s[28:29]
	s_cbranch_vccz .LBB0_305
	v_mov_b32_e32 v0, v200
	s_lshl_b32 s30, s48, 8
	s_load_dwordx2 s[42:43], s[22:23], 0xe8
	s_waitcnt lgkmcnt(0)
	v_bfe_u32 v176, v200, 6, 2
	v_bfe_u32 v177, v200, 5, 1
	v_lshlrev_b32_e32 v176, 6, v176
	v_lshl_or_b32 v176, v177, 2, v176
	v_add_u32_e32 v176, s30, v176
	v_lshlrev_b32_e32 v176, 2, v176
	global_load_dwordx4 v[144:147], v176, s[42:43]
	global_load_dwordx4 v[148:151], v176, s[42:43] offset:32
	global_load_dwordx4 v[152:155], v176, s[42:43] offset:64
	global_load_dwordx4 v[156:159], v176, s[42:43] offset:96
	global_load_dwordx4 v[160:163], v176, s[42:43] offset:128
	global_load_dwordx4 v[164:167], v176, s[42:43] offset:160
	global_load_dwordx4 v[168:171], v176, s[42:43] offset:192
	global_load_dwordx4 v[172:175], v176, s[42:43] offset:224
	v_ashrrev_i32_e32 v7, 6, v0
	v_lshrrev_b32_e32 v1, 4, v0
	v_bfe_u32 v5, v0, 2, 4
	v_xor_b32_e32 v1, v1, v0
	v_lshlrev_b32_e32 v4, 5, v7
	v_or_b32_e32 v12, v4, v5
	v_lshlrev_b32_e32 v1, 4, v1
	v_and_b32_e32 v6, 63, v0
	v_and_b32_e32 v2, 48, v1
	v_or_b32_e32 v1, 16, v12
	v_add_u32_e32 v8, s83, v12
	v_add_u32_e32 v10, s83, v1
	v_add_u32_e32 v14, s30, v1
	v_lshlrev_b32_e32 v1, 4, v6
	v_ashrrev_i32_e32 v9, 31, v8
	v_lshl_or_b32 v1, v7, 11, v1
	v_lshlrev_b64 v[8:9], 11, v[8:9]
	v_ashrrev_i32_e32 v11, 31, v10
	v_add_u32_e32 v12, s30, v12
	v_add_u32_e32 v18, 16, v1
	v_lshl_add_u64 v[8:9], s[62:63], 0, v[8:9]
	v_lshlrev_b64 v[10:11], 11, v[10:11]
	v_ashrrev_i32_e32 v13, 31, v12
	v_readfirstlane_b32 s24, v18
	v_add_u32_e32 v16, 0x400, v18
	v_lshl_add_u64 v[8:9], v[8:9], 0, v[2:3]
	v_lshl_add_u64 v[10:11], s[62:63], 0, v[10:11]
	v_lshlrev_b64 v[12:13], 11, v[12:13]
	v_ashrrev_i32_e32 v15, 31, v14
	s_mov_b32 m0, s24
	v_readfirstlane_b32 s24, v16
	v_add_u32_e32 v16, 0x4000, v18
	v_lshl_add_u64 v[10:11], v[10:11], 0, v[2:3]
	v_lshl_add_u64 v[12:13], s[64:65], 0, v[12:13]
	v_lshlrev_b64 v[14:15], 11, v[14:15]
	global_load_lds_dwordx4 v[8:9], off
	s_mov_b32 m0, s24
	v_readfirstlane_b32 s24, v16
	v_add_u32_e32 v16, 0x4400, v18
	v_lshl_add_u64 v[12:13], v[12:13], 0, v[2:3]
	v_lshl_add_u64 v[14:15], s[64:65], 0, v[14:15]
	global_load_lds_dwordx4 v[10:11], off
	s_mov_b32 m0, s24
	v_readfirstlane_b32 s24, v16
	v_add_u32_e32 v19, 0x8000, v18
	v_lshl_add_u64 v[14:15], v[14:15], 0, v[2:3]
	global_load_lds_dwordx4 v[12:13], off
	s_mov_b32 m0, s24
	v_readfirstlane_b32 s24, v19
	v_add_u32_e32 v19, 0x8400, v18
	global_load_lds_dwordx4 v[14:15], off
	v_lshl_add_u64 v[16:17], v[8:9], 0, 64
	s_mov_b32 m0, s24
	v_readfirstlane_b32 s24, v19
	v_add_u32_e32 v19, 0xc000, v18
	global_load_lds_dwordx4 v[16:17], off
	v_lshl_add_u64 v[16:17], v[10:11], 0, 64
	s_mov_b32 m0, s24
	v_readfirstlane_b32 s24, v19
	v_add_u32_e32 v18, 0xc400, v18
	global_load_lds_dwordx4 v[16:17], off
	v_lshl_add_u64 v[16:17], v[12:13], 0, 64
	s_mov_b32 m0, s24
	v_readfirstlane_b32 s24, v18
	global_load_lds_dwordx4 v[16:17], off
	v_lshl_add_u64 v[16:17], v[14:15], 0, 64
	s_mov_b32 m0, s24
	s_add_i32 s24, 16, 0x10000
	global_load_lds_dwordx4 v[16:17], off
	v_add_u32_e32 v16, s24, v1
	v_lshl_add_u64 v[8:9], v[8:9], 0, s[92:93]
	v_readfirstlane_b32 s24, v16
	s_mov_b32 m0, s24
	s_nop 0
	global_load_lds_dwordx4 v[8:9], off
	v_lshl_add_u64 v[8:9], v[10:11], 0, s[92:93]
	v_add_u32_e32 v10, 0x400, v16
	s_nop 0
	v_readfirstlane_b32 s24, v10
	v_add_u32_e32 v10, 0x4000, v16
	s_mov_b32 m0, s24
	v_readfirstlane_b32 s24, v10
	v_add_u32_e32 v10, 0x4400, v16
	global_load_lds_dwordx4 v[8:9], off
	v_lshl_add_u64 v[8:9], v[12:13], 0, s[92:93]
	s_mov_b32 m0, s24
	v_readfirstlane_b32 s24, v10
	global_load_lds_dwordx4 v[8:9], off
	v_lshl_add_u64 v[8:9], v[14:15], 0, s[92:93]
	s_mov_b32 m0, s24
	v_readfirstlane_b32 s24, v0
	global_load_lds_dwordx4 v[8:9], off
	s_waitcnt vmcnt(8)
	s_and_b32 s25, s24, 0xffffff00
	s_cmpk_lg_i32 s25, 0x100
	s_barrier
	s_cbranch_scc1 .LBB0_451
	s_barrier
.LBB0_451:
	v_lshrrev_b32_e32 v8, 30, v7
	v_add_u32_e32 v8, v7, v8
	v_ashrrev_i32_e32 v8, 2, v8
	v_mul_i32_i24_e32 v9, 4, v8
	v_lshrrev_b32_e32 v190, 5, v6
	v_lshrrev_b32_e32 v6, 2, v0
	v_sub_u32_e32 v7, v7, v9
	v_bfe_u32 v10, v0, 2, 2
	v_bitop3_b32 v6, v190, v6, 3 bitop3:0x78
	v_and_b32_e32 v9, 31, v0
	v_lshlrev_b32_e32 v0, 6, v7
	v_lshlrev_b32_e32 v193, 4, v6
	v_bitop3_b32 v6, v190, v10, 2 bitop3:0x36
	v_or_b32_e32 v7, v0, v9
	v_lshlrev_b32_e32 v194, 4, v6
	v_add3_u32 v6, v5, s83, v4
	v_lshlrev_b32_e32 v192, 6, v7
	v_ashrrev_i32_e32 v7, 31, v6
	v_lshlrev_b64 v[6:7], 11, v[6:7]
	v_lshl_or_b32 v182, v8, 7, v9
	v_or_b32_e32 v6, v6, v2
	v_or_b32_e32 v8, 16, v5
	v_lshl_add_u64 v[180:181], s[74:75], 0, v[6:7]
	v_add3_u32 v6, v8, s83, v4
	v_ashrrev_i32_e32 v7, 31, v6
	s_lshl_b32 s25, s35, 8
	v_lshlrev_b64 v[6:7], 11, v[6:7]
	v_or_b32_e32 v5, s25, v5
	v_or_b32_e32 v6, v6, v2
	v_add_u32_e32 v5, v5, v4
	v_lshl_add_u64 v[184:185], s[74:75], 0, v[6:7]
	v_subrev_u32_e32 v6, s34, v5
	v_or_b32_e32 v5, s25, v8
	v_add_u32_e32 v4, v5, v4
	v_subrev_u32_e32 v4, s34, v4
	v_ashrrev_i32_e32 v7, 31, v6
	v_ashrrev_i32_e32 v5, 31, v4
	v_lshlrev_b64 v[6:7], 11, v[6:7]
	v_lshlrev_b64 v[4:5], 11, v[4:5]
	v_or_b32_e32 v6, v6, v2
	v_or_b32_e32 v4, v4, v2
	v_mov_b32_e32 v116, v144
	v_lshlrev_b32_e32 v191, 6, v182
	v_lshl_add_u64 v[186:187], s[76:77], 0, v[6:7]
	v_lshl_add_u64 v[188:189], s[76:77], 0, v[4:5]
	s_mov_b32 s25, 0x18000
	s_mov_b32 s31, 0
	s_mov_b64 s[28:29], 0
	s_mov_b32 s36, 0
	v_mov_b32_e32 v117, v145
	v_mov_b32_e32 v118, v146
	v_mov_b32_e32 v119, v147
	v_mov_b32_e32 v120, v148
	v_mov_b32_e32 v121, v149
	v_mov_b32_e32 v122, v150
	v_mov_b32_e32 v123, v151
	v_mov_b32_e32 v124, v152
	v_mov_b32_e32 v125, v153
	v_mov_b32_e32 v126, v154
	v_mov_b32_e32 v127, v155
	v_mov_b32_e32 v128, v156
	v_mov_b32_e32 v129, v157
	v_mov_b32_e32 v130, v158
	v_mov_b32_e32 v131, v159
	v_mov_b32_e32 v100, v160
	v_mov_b32_e32 v101, v161
	v_mov_b32_e32 v102, v162
	v_mov_b32_e32 v103, v163
	v_mov_b32_e32 v104, v164
	v_mov_b32_e32 v105, v165
	v_mov_b32_e32 v106, v166
	v_mov_b32_e32 v107, v167
	v_mov_b32_e32 v108, v168
	v_mov_b32_e32 v109, v169
	v_mov_b32_e32 v110, v170
	v_mov_b32_e32 v111, v171
	v_mov_b32_e32 v112, v172
	v_mov_b32_e32 v113, v173
	v_mov_b32_e32 v114, v174
	v_mov_b32_e32 v115, v175
	v_mov_b32_e32 v84, v144
	v_mov_b32_e32 v85, v145
	v_mov_b32_e32 v86, v146
	v_mov_b32_e32 v87, v147
	v_mov_b32_e32 v88, v148
	v_mov_b32_e32 v89, v149
	v_mov_b32_e32 v90, v150
	v_mov_b32_e32 v91, v151
	v_mov_b32_e32 v92, v152
	v_mov_b32_e32 v93, v153
	v_mov_b32_e32 v94, v154
	v_mov_b32_e32 v95, v155
	v_mov_b32_e32 v96, v156
	v_mov_b32_e32 v97, v157
	v_mov_b32_e32 v98, v158
	v_mov_b32_e32 v99, v159
	v_mov_b32_e32 v68, v160
	v_mov_b32_e32 v69, v161
	v_mov_b32_e32 v70, v162
	v_mov_b32_e32 v71, v163
	v_mov_b32_e32 v72, v164
	v_mov_b32_e32 v73, v165
	v_mov_b32_e32 v74, v166
	v_mov_b32_e32 v75, v167
	v_mov_b32_e32 v76, v168
	v_mov_b32_e32 v77, v169
	v_mov_b32_e32 v78, v170
	v_mov_b32_e32 v79, v171
	v_mov_b32_e32 v80, v172
	v_mov_b32_e32 v81, v173
	v_mov_b32_e32 v82, v174
	v_mov_b32_e32 v83, v175
	v_mov_b32_e32 v52, v144
	v_mov_b32_e32 v53, v145
	v_mov_b32_e32 v54, v146
	v_mov_b32_e32 v55, v147
	v_mov_b32_e32 v56, v148
	v_mov_b32_e32 v57, v149
	v_mov_b32_e32 v58, v150
	v_mov_b32_e32 v59, v151
	v_mov_b32_e32 v60, v152
	v_mov_b32_e32 v61, v153
	v_mov_b32_e32 v62, v154
	v_mov_b32_e32 v63, v155
	v_mov_b32_e32 v64, v156
	v_mov_b32_e32 v65, v157
	v_mov_b32_e32 v66, v158
	v_mov_b32_e32 v67, v159
	v_mov_b32_e32 v36, v160
	v_mov_b32_e32 v37, v161
	v_mov_b32_e32 v38, v162
	v_mov_b32_e32 v39, v163
	v_mov_b32_e32 v40, v164
	v_mov_b32_e32 v41, v165
	v_mov_b32_e32 v42, v166
	v_mov_b32_e32 v43, v167
	v_mov_b32_e32 v44, v168
	v_mov_b32_e32 v45, v169
	v_mov_b32_e32 v46, v170
	v_mov_b32_e32 v47, v171
	v_mov_b32_e32 v48, v172
	v_mov_b32_e32 v49, v173
	v_mov_b32_e32 v50, v174
	v_mov_b32_e32 v51, v175
	v_mov_b32_e32 v20, v144
	v_mov_b32_e32 v21, v145
	v_mov_b32_e32 v22, v146
	v_mov_b32_e32 v23, v147
	v_mov_b32_e32 v24, v148
	v_mov_b32_e32 v25, v149
	v_mov_b32_e32 v26, v150
	v_mov_b32_e32 v27, v151
	v_mov_b32_e32 v28, v152
	v_mov_b32_e32 v29, v153
	v_mov_b32_e32 v30, v154
	v_mov_b32_e32 v31, v155
	v_mov_b32_e32 v32, v156
	v_mov_b32_e32 v33, v157
	v_mov_b32_e32 v34, v158
	v_mov_b32_e32 v35, v159
	v_mov_b32_e32 v4, v160
	v_mov_b32_e32 v5, v161
	v_mov_b32_e32 v6, v162
	v_mov_b32_e32 v7, v163
	v_mov_b32_e32 v8, v164
	v_mov_b32_e32 v9, v165
	v_mov_b32_e32 v10, v166
	v_mov_b32_e32 v11, v167
	v_mov_b32_e32 v12, v168
	v_mov_b32_e32 v13, v169
	v_mov_b32_e32 v14, v170
	v_mov_b32_e32 v15, v171
	v_mov_b32_e32 v16, v172
	v_mov_b32_e32 v17, v173
	v_mov_b32_e32 v18, v174
	v_mov_b32_e32 v19, v175
	s_branch .LBB0_453

.LBB0_461:
	s_load_dwordx2 s[34:35], s[22:23], 0xe8
	v_lshlrev_b32_e32 v136, 2, v190
	v_or_b32_e32 v1, v0, v136
	v_add_u32_e32 v138, s30, v1
	v_ashrrev_i32_e32 v139, 31, v138
	s_waitcnt lgkmcnt(0)
	v_lshl_add_u64 v[134:135], v[138:139], 2, s[34:35]
	v_and_b32_e32 v145, 0x9f, v182
	v_add_u32_e32 v140, s83, v182
	v_cmp_lt_i32_e32 vcc, s39, v138
	s_and_saveexec_b64 s[24:25], vcc
	s_xor_b64 s[28:29], exec, s[24:25]
	s_cbranch_execz .LBB0_465
	v_cmp_gt_i32_e64 s[42:43], s38, v140
	s_and_saveexec_b64 s[36:37], s[42:43]
	s_cbranch_execz .LBB0_464
	v_add_u32_e32 v2, 0xfffffc00, v138
	v_lshrrev_b32_e32 v132, 4, v140
	v_lshrrev_b32_e32 v2, 6, v2
	v_and_b32_e32 v132, 0xfffff0, v132
	v_add_u32_e32 v2, v132, v2
	v_lshl_or_b32 v132, v2, 8, v145
	v_ashrrev_i32_e32 v133, 31, v132
	v_lshlrev_b64 v[132:133], 8, v[132:133]
	v_lshl_add_u64 v[132:133], s[72:73], 0, v[132:133]
	v_lshlrev_b32_e32 v142, 2, v136
	v_mov_b32_e32 v143, v3
	v_lshl_add_u64 v[132:133], v[132:133], 0, v[142:143]
	global_store_dwordx4 v[132:133], v[116:119], off
	s_nop 1

.LBB0_465:
	s_andn2_saveexec_b64 s[28:29], s[28:29]
	v_pk_mul_f32 v[116:117], v[116:117], s[12:13] op_sel_hi:[1,0]
	v_pk_mul_f32 v[118:119], v[118:119], s[12:13] op_sel_hi:[1,0]
	s_or_b64 exec, exec, s[28:29]
	v_or_b32_e32 v139, 8, v1
	v_add_u32_e32 v144, s30, v139
	v_cmp_lt_i32_e64 s[42:43], s39, v144
	s_and_saveexec_b64 s[24:25], s[42:43]
	s_xor_b64 s[28:29], exec, s[24:25]
	s_cbranch_execz .LBB0_471
	v_cmp_gt_i32_e64 s[44:45], s38, v140
	s_and_saveexec_b64 s[36:37], s[44:45]
	s_cbranch_execz .LBB0_470
	v_add_u32_e32 v1, 0xfffffc00, v144
	v_lshrrev_b32_e32 v132, 4, v140
	v_lshrrev_b32_e32 v1, 6, v1
	v_and_b32_e32 v132, 0xfffff0, v132
	v_add_u32_e32 v1, v1, v132
	v_lshl_or_b32 v132, v1, 8, v145
	v_ashrrev_i32_e32 v133, 31, v132
	v_and_b32_e32 v2, 12, v139
	v_lshlrev_b64 v[132:133], 8, v[132:133]
	v_lshl_add_u64 v[132:133], s[72:73], 0, v[132:133]
	v_lshlrev_b32_e32 v142, 2, v2
	v_mov_b32_e32 v143, v3
	v_lshl_add_u64 v[132:133], v[132:133], 0, v[142:143]
	global_store_dwordx4 v[132:133], v[120:123], off
	s_nop 1

.LBB0_471:
	s_andn2_saveexec_b64 s[28:29], s[28:29]
	v_pk_mul_f32 v[120:121], v[120:121], s[12:13] op_sel_hi:[1,0]
	v_pk_mul_f32 v[122:123], v[122:123], s[12:13] op_sel_hi:[1,0]
	s_or_b64 exec, exec, s[28:29]
	s_ashr_i32 s31, s30, 31
	s_lshl_b64 s[24:25], s[30:31], 1
	s_add_u32 s28, s80, s24
	s_addc_u32 s29, s81, s25
	s_add_u32 s24, s60, s24
	s_addc_u32 s25, s61, s25
	s_add_u32 s24, s24, 0xd207800
	s_addc_u32 s25, s25, 0
	s_cmp_lt_i32 s48, 4
	v_ashrrev_i32_e32 v141, 31, v140
	v_cvt_pk_f16_f32 v146, v116, v117
	s_cselect_b32 s29, s29, s25
	s_cselect_b32 s28, s28, s24
	v_lshlrev_b64 v[116:117], 11, v[140:141]
	v_lshl_add_u64 v[116:117], s[28:29], 0, v[116:117]
	v_ashrrev_i32_e32 v1, 31, v0
	v_lshl_add_u64 v[116:117], v[0:1], 1, v[116:117]
	v_lshlrev_b32_e32 v2, 4, v190
	v_mov_b32_e32 v137, v3
	v_cvt_pk_f16_f32 v147, v118, v119
	v_cvt_pk_f16_f32 v149, v122, v123
	v_cvt_pk_f16_f32 v148, v120, v121
	v_lshl_add_u64 v[142:143], v[116:117], 0, v[2:3]
	v_lshl_add_u64 v[116:117], v[0:1], 0, v[136:137]
	v_permlane32_swap_b32_e32 v146, v148
	v_permlane32_swap_b32_e32 v147, v149
	v_lshl_add_u64 v[116:117], v[116:117], 0, s[30:31]
	global_store_dwordx4 v[142:143], v[146:149], off
	s_nop 1
	v_lshl_add_u64 v[132:133], v[116:117], 2, s[34:35]
	v_or3_b32 v137, v0, v136, 16
	v_add_u32_e32 v141, s30, v137
	v_cmp_lt_i32_e64 s[44:45], s39, v141
	v_mov_b32_e32 v116, v124
	v_mov_b32_e32 v117, v125
	v_mov_b32_e32 v118, v126
	v_mov_b32_e32 v119, v127
	s_and_saveexec_b64 s[24:25], s[44:45]
	s_xor_b64 s[34:35], exec, s[24:25]
	s_cbranch_execz .LBB0_477
	v_cmp_gt_i32_e64 s[46:47], s38, v140
	s_and_saveexec_b64 s[36:37], s[46:47]
	s_cbranch_execz .LBB0_476
	v_add_u32_e32 v2, 0xfffffc00, v141
	v_lshrrev_b32_e32 v120, 4, v140
	v_lshrrev_b32_e32 v2, 6, v2
	v_and_b32_e32 v120, 0xfffff0, v120
	v_add_u32_e32 v2, v2, v120
	v_lshl_or_b32 v120, v2, 8, v145
	v_ashrrev_i32_e32 v121, 31, v120
	v_and_b32_e32 v122, 20, v137
	v_lshlrev_b64 v[120:121], 8, v[120:121]
	v_lshl_add_u64 v[120:121], s[72:73], 0, v[120:121]
	v_lshlrev_b32_e32 v122, 2, v122
	v_mov_b32_e32 v123, v3
	v_lshl_add_u64 v[120:121], v[120:121], 0, v[122:123]
	global_store_dwordx4 v[120:121], v[116:119], off
	s_nop 1

.LBB0_477:
	s_andn2_saveexec_b64 s[34:35], s[34:35]
	v_pk_mul_f32 v[116:117], v[116:117], s[12:13] op_sel_hi:[1,0]
	v_pk_mul_f32 v[118:119], v[118:119], s[12:13] op_sel_hi:[1,0]
	s_or_b64 exec, exec, s[34:35]
	v_or_b32_e32 v124, 8, v137
	v_add_u32_e32 v125, s30, v124
	v_cmp_lt_i32_e64 s[46:47], s39, v125
	v_mov_b32_e32 v120, v128
	v_mov_b32_e32 v121, v129
	v_mov_b32_e32 v122, v130
	v_mov_b32_e32 v123, v131
	s_and_saveexec_b64 s[24:25], s[46:47]
	s_xor_b64 s[34:35], exec, s[24:25]
	s_cbranch_execz .LBB0_483
	v_cmp_gt_i32_e64 s[48:49], s38, v140
	s_and_saveexec_b64 s[36:37], s[48:49]
	s_cbranch_execz .LBB0_482
	v_add_u32_e32 v2, 0xfffffc00, v125
	v_lshrrev_b32_e32 v126, 4, v140
	v_lshrrev_b32_e32 v2, 6, v2
	v_and_b32_e32 v126, 0xfffff0, v126
	v_add_u32_e32 v2, v2, v126
	v_lshl_or_b32 v126, v2, 8, v145
	v_ashrrev_i32_e32 v127, 31, v126
	v_and_b32_e32 v128, 28, v124
	v_lshlrev_b64 v[126:127], 8, v[126:127]
	v_lshl_add_u64 v[126:127], s[72:73], 0, v[126:127]
	v_lshlrev_b32_e32 v128, 2, v128
	v_mov_b32_e32 v129, v3
	v_lshl_add_u64 v[126:127], v[126:127], 0, v[128:129]
	global_store_dwordx4 v[126:127], v[120:123], off
	s_nop 1

.LBB0_483:
	s_andn2_saveexec_b64 s[34:35], s[34:35]
	v_pk_mul_f32 v[120:121], v[120:121], s[12:13] op_sel_hi:[1,0]
	v_pk_mul_f32 v[122:123], v[122:123], s[12:13] op_sel_hi:[1,0]
	s_or_b64 exec, exec, s[34:35]
	v_cvt_pk_f16_f32 v127, v118, v119
	v_cvt_pk_f16_f32 v126, v116, v117
	v_cvt_pk_f16_f32 v129, v122, v123
	v_cvt_pk_f16_f32 v128, v120, v121
	s_nop 1
	v_permlane32_swap_b32_e32 v126, v128
	v_permlane32_swap_b32_e32 v127, v129
	global_store_dwordx4 v[142:143], v[126:129], off offset:32
	s_nop 1
	v_or3_b32 v116, v0, v136, 32
	v_add_u32_e32 v117, s30, v116
	v_cmp_lt_i32_e64 s[48:49], s39, v117
	s_and_saveexec_b64 s[24:25], s[48:49]
	s_xor_b64 s[34:35], exec, s[24:25]
	s_cbranch_execz .LBB0_489
	v_cmp_gt_i32_e64 s[50:51], s38, v140
	s_and_saveexec_b64 s[36:37], s[50:51]
	s_cbranch_execz .LBB0_488
	v_add_u32_e32 v2, 0xfffffc00, v117
	v_lshrrev_b32_e32 v118, 4, v140
	v_lshrrev_b32_e32 v2, 6, v2
	v_and_b32_e32 v118, 0xfffff0, v118
	v_add_u32_e32 v2, v2, v118
	v_lshl_or_b32 v118, v2, 8, v145
	v_ashrrev_i32_e32 v119, 31, v118
	v_and_b32_e32 v120, 36, v116
	v_lshlrev_b64 v[118:119], 8, v[118:119]
	v_lshl_add_u64 v[118:119], s[72:73], 0, v[118:119]
	v_lshlrev_b32_e32 v120, 2, v120
	v_mov_b32_e32 v121, v3
	v_lshl_add_u64 v[118:119], v[118:119], 0, v[120:121]
	global_store_dwordx4 v[118:119], v[100:103], off
	s_nop 1

.LBB0_489:
	s_andn2_saveexec_b64 s[34:35], s[34:35]
	v_pk_mul_f32 v[100:101], v[100:101], s[12:13] op_sel_hi:[1,0]
	v_pk_mul_f32 v[102:103], v[102:103], s[12:13] op_sel_hi:[1,0]
	s_or_b64 exec, exec, s[34:35]
	v_or_b32_e32 v118, 8, v116
	v_add_u32_e32 v119, s30, v118
	v_cmp_lt_i32_e64 s[50:51], s39, v119
	s_and_saveexec_b64 s[24:25], s[50:51]
	s_xor_b64 s[34:35], exec, s[24:25]
	s_cbranch_execz .LBB0_495
	v_cmp_gt_i32_e64 s[52:53], s38, v140
	s_and_saveexec_b64 s[36:37], s[52:53]
	s_cbranch_execz .LBB0_494
	v_add_u32_e32 v2, 0xfffffc00, v119
	v_lshrrev_b32_e32 v120, 4, v140
	v_lshrrev_b32_e32 v2, 6, v2
	v_and_b32_e32 v120, 0xfffff0, v120
	v_add_u32_e32 v2, v2, v120
	v_lshl_or_b32 v120, v2, 8, v145
	v_ashrrev_i32_e32 v121, 31, v120
	v_and_b32_e32 v122, 44, v118
	v_lshlrev_b64 v[120:121], 8, v[120:121]
	v_lshl_add_u64 v[120:121], s[72:73], 0, v[120:121]
	v_lshlrev_b32_e32 v122, 2, v122
	v_mov_b32_e32 v123, v3
	v_lshl_add_u64 v[120:121], v[120:121], 0, v[122:123]
	global_store_dwordx4 v[120:121], v[104:107], off
	s_nop 1

.LBB0_495:
	s_andn2_saveexec_b64 s[34:35], s[34:35]
	v_pk_mul_f32 v[104:105], v[104:105], s[12:13] op_sel_hi:[1,0]
	v_pk_mul_f32 v[106:107], v[106:107], s[12:13] op_sel_hi:[1,0]
	s_or_b64 exec, exec, s[34:35]
	v_cvt_pk_f16_f32 v121, v102, v103
	v_cvt_pk_f16_f32 v120, v100, v101
	v_cvt_pk_f16_f32 v123, v106, v107
	v_cvt_pk_f16_f32 v122, v104, v105
	s_nop 1
	v_permlane32_swap_b32_e32 v120, v122
	v_permlane32_swap_b32_e32 v121, v123
	global_store_dwordx4 v[142:143], v[120:123], off offset:64
	s_nop 1
	v_mov_b32_e32 v100, v108
	v_mov_b32_e32 v101, v109
	v_or3_b32 v120, v0, v136, 48
	v_add_u32_e32 v121, s30, v120
	v_mov_b32_e32 v102, v110
	v_mov_b32_e32 v103, v111
	v_cmp_lt_i32_e64 s[52:53], s39, v121
	s_and_saveexec_b64 s[24:25], s[52:53]
	s_xor_b64 s[34:35], exec, s[24:25]
	s_cbranch_execz .LBB0_501
	v_cmp_gt_i32_e64 s[54:55], s38, v140
	s_and_saveexec_b64 s[36:37], s[54:55]
	s_cbranch_execz .LBB0_500
	v_add_u32_e32 v2, 0xfffffc00, v121
	v_lshrrev_b32_e32 v104, 4, v140
	v_lshrrev_b32_e32 v2, 6, v2
	v_and_b32_e32 v104, 0xfffff0, v104
	v_add_u32_e32 v2, v2, v104
	v_lshl_or_b32 v104, v2, 8, v145
	v_ashrrev_i32_e32 v105, 31, v104
	v_and_b32_e32 v106, 52, v120
	v_lshlrev_b64 v[104:105], 8, v[104:105]
	v_lshl_add_u64 v[104:105], s[72:73], 0, v[104:105]
	v_lshlrev_b32_e32 v106, 2, v106
	v_mov_b32_e32 v107, v3
	v_lshl_add_u64 v[104:105], v[104:105], 0, v[106:107]
	global_store_dwordx4 v[104:105], v[100:103], off
	s_nop 1

.LBB0_501:
	s_andn2_saveexec_b64 s[34:35], s[34:35]
	v_pk_mul_f32 v[100:101], v[100:101], s[12:13] op_sel_hi:[1,0]
	v_pk_mul_f32 v[102:103], v[102:103], s[12:13] op_sel_hi:[1,0]
	s_or_b64 exec, exec, s[34:35]
	v_or_b32_e32 v108, 8, v120
	v_add_u32_e32 v109, s30, v108
	v_cmp_lt_i32_e64 s[54:55], s39, v109
	v_mov_b32_e32 v104, v112
	v_mov_b32_e32 v105, v113
	v_mov_b32_e32 v106, v114
	v_mov_b32_e32 v107, v115
	s_and_saveexec_b64 s[24:25], s[54:55]
	s_xor_b64 s[30:31], exec, s[24:25]
	s_cbranch_execz .LBB0_507
	v_cmp_gt_i32_e64 s[56:57], s38, v140
	s_and_saveexec_b64 s[34:35], s[56:57]
	s_cbranch_execz .LBB0_506
	v_add_u32_e32 v2, 0xfffffc00, v109
	v_lshrrev_b32_e32 v110, 4, v140
	v_lshrrev_b32_e32 v2, 6, v2
	v_and_b32_e32 v110, 0xfffff0, v110
	v_add_u32_e32 v2, v2, v110
	v_lshl_or_b32 v110, v2, 8, v145
	v_ashrrev_i32_e32 v111, 31, v110
	v_and_b32_e32 v112, 60, v108
	v_lshlrev_b64 v[110:111], 8, v[110:111]
	v_lshl_add_u64 v[110:111], s[72:73], 0, v[110:111]
	v_lshlrev_b32_e32 v112, 2, v112
	v_mov_b32_e32 v113, v3
	v_lshl_add_u64 v[110:111], v[110:111], 0, v[112:113]
	global_store_dwordx4 v[110:111], v[104:107], off
	s_nop 1

.LBB0_507:
	s_andn2_saveexec_b64 s[30:31], s[30:31]
	v_pk_mul_f32 v[104:105], v[104:105], s[12:13] op_sel_hi:[1,0]
	v_pk_mul_f32 v[106:107], v[106:107], s[12:13] op_sel_hi:[1,0]
	s_or_b64 exec, exec, s[30:31]
	v_cvt_pk_f16_f32 v111, v102, v103
	v_cvt_pk_f16_f32 v110, v100, v101
	v_cvt_pk_f16_f32 v113, v106, v107
	v_cvt_pk_f16_f32 v112, v104, v105
	s_nop 1
	v_permlane32_swap_b32_e32 v110, v112
	v_permlane32_swap_b32_e32 v111, v113
	global_store_dwordx4 v[142:143], v[110:113], off offset:96
	s_nop 1
	v_or_b32_e32 v2, 32, v182
	s_movk_i32 s24, 0xbf
	v_bitop3_b32 v104, v182, s24, 32 bitop3:0xc8
	v_add_u32_e32 v100, s83, v2
	s_and_saveexec_b64 s[24:25], vcc
	s_xor_b64 s[30:31], exec, s[24:25]
	s_cbranch_execz .LBB0_513
	v_cmp_gt_i32_e64 s[56:57], s38, v100
	s_and_saveexec_b64 s[34:35], s[56:57]
	s_cbranch_execz .LBB0_512
	v_add_u32_e32 v2, 0xfffffc00, v138
	v_lshrrev_b32_e32 v101, 4, v100
	v_lshrrev_b32_e32 v2, 6, v2
	v_and_b32_e32 v101, 0xfffff0, v101
	v_add_u32_e32 v2, v101, v2
	v_lshl_or_b32 v102, v2, 8, v104
	v_ashrrev_i32_e32 v103, 31, v102
	v_lshlrev_b64 v[102:103], 8, v[102:103]
	v_lshl_add_u64 v[102:103], s[72:73], 0, v[102:103]
	v_lshlrev_b32_e32 v106, 2, v136
	v_mov_b32_e32 v107, v3
	v_lshl_add_u64 v[102:103], v[102:103], 0, v[106:107]
	global_store_dwordx4 v[102:103], v[84:87], off
	s_nop 1

.LBB0_513:
	s_andn2_saveexec_b64 s[30:31], s[30:31]
	v_pk_mul_f32 v[84:85], v[84:85], s[12:13] op_sel_hi:[1,0]
	v_pk_mul_f32 v[86:87], v[86:87], s[12:13] op_sel_hi:[1,0]
	s_or_b64 exec, exec, s[30:31]
	s_and_saveexec_b64 s[24:25], s[42:43]
	s_xor_b64 s[30:31], exec, s[24:25]
	s_cbranch_execz .LBB0_519
	v_cmp_gt_i32_e64 s[56:57], s38, v100
	s_and_saveexec_b64 s[34:35], s[56:57]
	s_cbranch_execz .LBB0_518
	v_add_u32_e32 v2, 0xfffffc00, v144
	v_lshrrev_b32_e32 v102, 4, v100
	v_lshrrev_b32_e32 v2, 6, v2
	v_and_b32_e32 v102, 0xfffff0, v102
	v_add_u32_e32 v2, v102, v2
	v_lshl_or_b32 v102, v2, 8, v104
	v_ashrrev_i32_e32 v103, 31, v102
	v_and_b32_e32 v101, 12, v139
	v_lshlrev_b64 v[102:103], 8, v[102:103]
	v_lshl_add_u64 v[102:103], s[72:73], 0, v[102:103]
	v_lshlrev_b32_e32 v106, 2, v101
	v_mov_b32_e32 v107, v3
	v_lshl_add_u64 v[102:103], v[102:103], 0, v[106:107]
	global_store_dwordx4 v[102:103], v[88:91], off
	s_nop 1

.LBB0_519:
	s_andn2_saveexec_b64 s[30:31], s[30:31]
	v_pk_mul_f32 v[88:89], v[88:89], s[12:13] op_sel_hi:[1,0]
	v_pk_mul_f32 v[90:91], v[90:91], s[12:13] op_sel_hi:[1,0]
	s_or_b64 exec, exec, s[30:31]
	v_ashrrev_i32_e32 v101, 31, v100
	v_cvt_pk_f16_f32 v110, v84, v85
	v_lshlrev_b64 v[84:85], 11, v[100:101]
	v_lshlrev_b32_e32 v2, 3, v190
	v_lshl_add_u64 v[84:85], s[28:29], 0, v[84:85]
	v_cvt_pk_f16_f32 v111, v86, v87
	v_cvt_pk_f16_f32 v113, v90, v91
	v_cvt_pk_f16_f32 v112, v88, v89
	v_lshl_add_u64 v[84:85], v[0:1], 1, v[84:85]
	v_lshlrev_b32_e32 v2, 1, v2
	v_permlane32_swap_b32_e32 v110, v112
	v_permlane32_swap_b32_e32 v111, v113
	v_lshl_add_u64 v[102:103], v[84:85], 0, v[2:3]
	global_store_dwordx4 v[102:103], v[110:113], off
	s_nop 1
	v_mov_b32_e32 v84, v92
	v_mov_b32_e32 v85, v93
	v_mov_b32_e32 v86, v94
	v_mov_b32_e32 v87, v95
	s_and_saveexec_b64 s[24:25], s[44:45]
	s_xor_b64 s[30:31], exec, s[24:25]
	s_cbranch_execz .LBB0_525
	v_cmp_gt_i32_e64 s[56:57], s38, v100
	s_and_saveexec_b64 s[34:35], s[56:57]
	s_cbranch_execz .LBB0_524
	v_add_u32_e32 v88, 0xfffffc00, v141
	v_lshrrev_b32_e32 v89, 4, v100
	v_lshrrev_b32_e32 v88, 6, v88
	v_and_b32_e32 v89, 0xfffff0, v89
	v_add_u32_e32 v88, v89, v88
	v_lshl_or_b32 v88, v88, 8, v104
	v_ashrrev_i32_e32 v89, 31, v88
	v_and_b32_e32 v90, 20, v137
	v_lshlrev_b64 v[88:89], 8, v[88:89]
	v_lshl_add_u64 v[88:89], s[72:73], 0, v[88:89]
	v_lshlrev_b32_e32 v90, 2, v90
	v_mov_b32_e32 v91, v3
	v_lshl_add_u64 v[88:89], v[88:89], 0, v[90:91]
	global_store_dwordx4 v[88:89], v[84:87], off
	s_nop 1

.LBB0_525:
	s_andn2_saveexec_b64 s[30:31], s[30:31]
	v_pk_mul_f32 v[84:85], v[84:85], s[12:13] op_sel_hi:[1,0]
	v_pk_mul_f32 v[86:87], v[86:87], s[12:13] op_sel_hi:[1,0]
	s_or_b64 exec, exec, s[30:31]
	v_mov_b32_e32 v88, v96
	v_mov_b32_e32 v89, v97
	v_mov_b32_e32 v90, v98
	v_mov_b32_e32 v91, v99
	s_and_saveexec_b64 s[24:25], s[46:47]
	s_xor_b64 s[30:31], exec, s[24:25]
	s_cbranch_execz .LBB0_531
	v_cmp_gt_i32_e64 s[56:57], s38, v100
	s_and_saveexec_b64 s[34:35], s[56:57]
	s_cbranch_execz .LBB0_530
	v_add_u32_e32 v92, 0xfffffc00, v125
	v_lshrrev_b32_e32 v93, 4, v100
	v_lshrrev_b32_e32 v92, 6, v92
	v_and_b32_e32 v93, 0xfffff0, v93
	v_add_u32_e32 v92, v92, v93
	v_lshl_or_b32 v92, v92, 8, v104
	v_ashrrev_i32_e32 v93, 31, v92
	v_and_b32_e32 v94, 28, v124
	v_lshlrev_b64 v[92:93], 8, v[92:93]
	v_lshl_add_u64 v[92:93], s[72:73], 0, v[92:93]
	v_lshlrev_b32_e32 v94, 2, v94
	v_mov_b32_e32 v95, v3
	v_lshl_add_u64 v[92:93], v[92:93], 0, v[94:95]
	global_store_dwordx4 v[92:93], v[88:91], off
	s_nop 1

.LBB0_531:
	s_andn2_saveexec_b64 s[30:31], s[30:31]
	v_pk_mul_f32 v[88:89], v[88:89], s[12:13] op_sel_hi:[1,0]
	v_pk_mul_f32 v[90:91], v[90:91], s[12:13] op_sel_hi:[1,0]
	s_or_b64 exec, exec, s[30:31]
	v_cvt_pk_f16_f32 v93, v86, v87
	v_cvt_pk_f16_f32 v92, v84, v85
	v_cvt_pk_f16_f32 v95, v90, v91
	v_cvt_pk_f16_f32 v94, v88, v89
	s_nop 1
	v_permlane32_swap_b32_e32 v92, v94
	v_permlane32_swap_b32_e32 v93, v95
	global_store_dwordx4 v[102:103], v[92:95], off offset:32
	s_nop 1
	s_and_saveexec_b64 s[24:25], s[48:49]
	s_xor_b64 s[30:31], exec, s[24:25]
	s_cbranch_execz .LBB0_537
	v_cmp_gt_i32_e64 s[56:57], s38, v100
	s_and_saveexec_b64 s[34:35], s[56:57]
	s_cbranch_execz .LBB0_536
	v_add_u32_e32 v84, 0xfffffc00, v117
	v_lshrrev_b32_e32 v85, 4, v100
	v_lshrrev_b32_e32 v84, 6, v84
	v_and_b32_e32 v85, 0xfffff0, v85
	v_add_u32_e32 v84, v85, v84
	v_lshl_or_b32 v84, v84, 8, v104
	v_ashrrev_i32_e32 v85, 31, v84
	v_and_b32_e32 v86, 36, v116
	v_lshlrev_b64 v[84:85], 8, v[84:85]
	v_lshl_add_u64 v[84:85], s[72:73], 0, v[84:85]
	v_lshlrev_b32_e32 v86, 2, v86
	v_mov_b32_e32 v87, v3
	v_lshl_add_u64 v[84:85], v[84:85], 0, v[86:87]
	global_store_dwordx4 v[84:85], v[68:71], off
	s_nop 1

.LBB0_537:
	s_andn2_saveexec_b64 s[30:31], s[30:31]
	v_pk_mul_f32 v[68:69], v[68:69], s[12:13] op_sel_hi:[1,0]
	v_pk_mul_f32 v[70:71], v[70:71], s[12:13] op_sel_hi:[1,0]
	s_or_b64 exec, exec, s[30:31]
	s_and_saveexec_b64 s[24:25], s[50:51]
	s_xor_b64 s[30:31], exec, s[24:25]
	s_cbranch_execz .LBB0_543
	v_cmp_gt_i32_e64 s[56:57], s38, v100
	s_and_saveexec_b64 s[34:35], s[56:57]
	s_cbranch_execz .LBB0_542
	v_add_u32_e32 v84, 0xfffffc00, v119
	v_lshrrev_b32_e32 v85, 4, v100
	v_lshrrev_b32_e32 v84, 6, v84
	v_and_b32_e32 v85, 0xfffff0, v85
	v_add_u32_e32 v84, v84, v85
	v_lshl_or_b32 v84, v84, 8, v104
	v_ashrrev_i32_e32 v85, 31, v84
	v_and_b32_e32 v86, 44, v118
	v_lshlrev_b64 v[84:85], 8, v[84:85]
	v_lshl_add_u64 v[84:85], s[72:73], 0, v[84:85]
	v_lshlrev_b32_e32 v86, 2, v86
	v_mov_b32_e32 v87, v3
	v_lshl_add_u64 v[84:85], v[84:85], 0, v[86:87]
	global_store_dwordx4 v[84:85], v[72:75], off
	s_nop 1

.LBB0_543:
	s_andn2_saveexec_b64 s[30:31], s[30:31]
	v_pk_mul_f32 v[72:73], v[72:73], s[12:13] op_sel_hi:[1,0]
	v_pk_mul_f32 v[74:75], v[74:75], s[12:13] op_sel_hi:[1,0]
	s_or_b64 exec, exec, s[30:31]
	v_cvt_pk_f16_f32 v85, v70, v71
	v_cvt_pk_f16_f32 v84, v68, v69
	v_cvt_pk_f16_f32 v87, v74, v75
	v_cvt_pk_f16_f32 v86, v72, v73
	s_nop 1
	v_permlane32_swap_b32_e32 v84, v86
	v_permlane32_swap_b32_e32 v85, v87
	global_store_dwordx4 v[102:103], v[84:87], off offset:64
	s_nop 1
	v_mov_b32_e32 v68, v76
	v_mov_b32_e32 v69, v77
	v_mov_b32_e32 v70, v78
	v_mov_b32_e32 v71, v79
	s_and_saveexec_b64 s[24:25], s[52:53]
	s_xor_b64 s[30:31], exec, s[24:25]
	s_cbranch_execz .LBB0_549
	v_cmp_gt_i32_e64 s[56:57], s38, v100
	s_and_saveexec_b64 s[34:35], s[56:57]
	s_cbranch_execz .LBB0_548
	v_add_u32_e32 v72, 0xfffffc00, v121
	v_lshrrev_b32_e32 v73, 4, v100
	v_lshrrev_b32_e32 v72, 6, v72
	v_and_b32_e32 v73, 0xfffff0, v73
	v_add_u32_e32 v72, v73, v72
	v_lshl_or_b32 v72, v72, 8, v104
	v_ashrrev_i32_e32 v73, 31, v72
	v_and_b32_e32 v74, 52, v120
	v_lshlrev_b64 v[72:73], 8, v[72:73]
	v_lshl_add_u64 v[72:73], s[72:73], 0, v[72:73]
	v_lshlrev_b32_e32 v74, 2, v74
	v_mov_b32_e32 v75, v3
	v_lshl_add_u64 v[72:73], v[72:73], 0, v[74:75]
	global_store_dwordx4 v[72:73], v[68:71], off
	s_nop 1

.LBB0_549:
	s_andn2_saveexec_b64 s[30:31], s[30:31]
	v_pk_mul_f32 v[68:69], v[68:69], s[12:13] op_sel_hi:[1,0]
	v_pk_mul_f32 v[70:71], v[70:71], s[12:13] op_sel_hi:[1,0]
	s_or_b64 exec, exec, s[30:31]
	v_mov_b32_e32 v72, v80
	v_mov_b32_e32 v73, v81
	v_mov_b32_e32 v74, v82
	v_mov_b32_e32 v75, v83
	s_and_saveexec_b64 s[24:25], s[54:55]
	s_xor_b64 s[30:31], exec, s[24:25]
	s_cbranch_execz .LBB0_555
	v_cmp_gt_i32_e64 s[56:57], s38, v100
	s_and_saveexec_b64 s[34:35], s[56:57]
	s_cbranch_execz .LBB0_554
	v_add_u32_e32 v76, 0xfffffc00, v109
	v_lshrrev_b32_e32 v77, 4, v100
	v_lshrrev_b32_e32 v76, 6, v76
	v_and_b32_e32 v77, 0xfffff0, v77
	v_add_u32_e32 v76, v76, v77
	v_lshl_or_b32 v76, v76, 8, v104
	v_ashrrev_i32_e32 v77, 31, v76
	v_and_b32_e32 v78, 60, v108
	v_lshlrev_b64 v[76:77], 8, v[76:77]
	v_lshl_add_u64 v[76:77], s[72:73], 0, v[76:77]
	v_lshlrev_b32_e32 v78, 2, v78
	v_mov_b32_e32 v79, v3
	v_lshl_add_u64 v[76:77], v[76:77], 0, v[78:79]
	global_store_dwordx4 v[76:77], v[72:75], off
	s_nop 1

.LBB0_555:
	s_andn2_saveexec_b64 s[30:31], s[30:31]
	v_pk_mul_f32 v[72:73], v[72:73], s[12:13] op_sel_hi:[1,0]
	v_pk_mul_f32 v[74:75], v[74:75], s[12:13] op_sel_hi:[1,0]
	s_or_b64 exec, exec, s[30:31]
	v_cvt_pk_f16_f32 v77, v70, v71
	v_cvt_pk_f16_f32 v76, v68, v69
	v_cvt_pk_f16_f32 v79, v74, v75
	v_cvt_pk_f16_f32 v78, v72, v73
	s_nop 1
	v_permlane32_swap_b32_e32 v76, v78
	v_permlane32_swap_b32_e32 v77, v79
	global_store_dwordx4 v[102:103], v[76:79], off offset:96
	s_nop 1
	v_or_b32_e32 v68, 64, v182
	s_movk_i32 s24, 0xdf
	v_bitop3_b32 v72, v182, s24, 64 bitop3:0xc8
	v_add_u32_e32 v68, s83, v68
	s_and_saveexec_b64 s[24:25], vcc
	s_xor_b64 s[30:31], exec, s[24:25]
	s_cbranch_execz .LBB0_561
	v_cmp_gt_i32_e64 s[56:57], s38, v68
	s_and_saveexec_b64 s[34:35], s[56:57]
	s_cbranch_execz .LBB0_560
	v_add_u32_e32 v69, 0xfffffc00, v138
	v_lshrrev_b32_e32 v70, 4, v68
	v_lshrrev_b32_e32 v69, 6, v69
	v_and_b32_e32 v70, 0xfffff0, v70
	v_add_u32_e32 v69, v70, v69
	v_lshl_or_b32 v70, v69, 8, v72
	v_ashrrev_i32_e32 v71, 31, v70
	v_lshlrev_b64 v[70:71], 8, v[70:71]
	v_lshl_add_u64 v[70:71], s[72:73], 0, v[70:71]
	v_lshlrev_b32_e32 v74, 2, v136
	v_mov_b32_e32 v75, v3
	v_lshl_add_u64 v[70:71], v[70:71], 0, v[74:75]
	global_store_dwordx4 v[70:71], v[52:55], off
	s_nop 1

.LBB0_561:
	s_andn2_saveexec_b64 s[30:31], s[30:31]
	v_pk_mul_f32 v[52:53], v[52:53], s[12:13] op_sel_hi:[1,0]
	v_pk_mul_f32 v[54:55], v[54:55], s[12:13] op_sel_hi:[1,0]
	s_or_b64 exec, exec, s[30:31]
	s_and_saveexec_b64 s[24:25], s[42:43]
	s_xor_b64 s[30:31], exec, s[24:25]
	s_cbranch_execz .LBB0_567
	v_cmp_gt_i32_e64 s[56:57], s38, v68
	s_and_saveexec_b64 s[34:35], s[56:57]
	s_cbranch_execz .LBB0_566
	v_add_u32_e32 v69, 0xfffffc00, v144
	v_lshrrev_b32_e32 v70, 4, v68
	v_lshrrev_b32_e32 v69, 6, v69
	v_and_b32_e32 v70, 0xfffff0, v70
	v_add_u32_e32 v69, v70, v69
	v_lshl_or_b32 v70, v69, 8, v72
	v_ashrrev_i32_e32 v71, 31, v70
	v_and_b32_e32 v73, 12, v139
	v_lshlrev_b64 v[70:71], 8, v[70:71]
	v_lshl_add_u64 v[70:71], s[72:73], 0, v[70:71]
	v_lshlrev_b32_e32 v74, 2, v73
	v_mov_b32_e32 v75, v3
	v_lshl_add_u64 v[70:71], v[70:71], 0, v[74:75]
	global_store_dwordx4 v[70:71], v[56:59], off
	s_nop 1

.LBB0_567:
	s_andn2_saveexec_b64 s[30:31], s[30:31]
	v_pk_mul_f32 v[56:57], v[56:57], s[12:13] op_sel_hi:[1,0]
	v_pk_mul_f32 v[58:59], v[58:59], s[12:13] op_sel_hi:[1,0]
	s_or_b64 exec, exec, s[30:31]
	v_ashrrev_i32_e32 v69, 31, v68
	v_cvt_pk_f16_f32 v74, v52, v53
	v_lshlrev_b64 v[52:53], 11, v[68:69]
	v_lshl_add_u64 v[52:53], s[28:29], 0, v[52:53]
	v_cvt_pk_f16_f32 v75, v54, v55
	v_cvt_pk_f16_f32 v77, v58, v59
	v_cvt_pk_f16_f32 v76, v56, v57
	v_lshl_add_u64 v[52:53], v[0:1], 1, v[52:53]
	s_nop 0
	v_permlane32_swap_b32_e32 v74, v76
	v_permlane32_swap_b32_e32 v75, v77
	v_lshl_add_u64 v[70:71], v[52:53], 0, v[2:3]
	global_store_dwordx4 v[70:71], v[74:77], off
	s_nop 1
	v_mov_b32_e32 v52, v60
	v_mov_b32_e32 v53, v61
	v_mov_b32_e32 v54, v62
	v_mov_b32_e32 v55, v63
	s_and_saveexec_b64 s[24:25], s[44:45]
	s_xor_b64 s[30:31], exec, s[24:25]
	s_cbranch_execz .LBB0_573
	v_cmp_gt_i32_e64 s[56:57], s38, v68
	s_and_saveexec_b64 s[34:35], s[56:57]
	s_cbranch_execz .LBB0_572
	v_add_u32_e32 v56, 0xfffffc00, v141
	v_lshrrev_b32_e32 v57, 4, v68
	v_lshrrev_b32_e32 v56, 6, v56
	v_and_b32_e32 v57, 0xfffff0, v57
	v_add_u32_e32 v56, v57, v56
	v_lshl_or_b32 v56, v56, 8, v72
	v_ashrrev_i32_e32 v57, 31, v56
	v_and_b32_e32 v58, 20, v137
	v_lshlrev_b64 v[56:57], 8, v[56:57]
	v_lshl_add_u64 v[56:57], s[72:73], 0, v[56:57]
	v_lshlrev_b32_e32 v58, 2, v58
	v_mov_b32_e32 v59, v3
	v_lshl_add_u64 v[56:57], v[56:57], 0, v[58:59]
	global_store_dwordx4 v[56:57], v[52:55], off
	s_nop 1

.LBB0_573:
	s_andn2_saveexec_b64 s[30:31], s[30:31]
	v_pk_mul_f32 v[52:53], v[52:53], s[12:13] op_sel_hi:[1,0]
	v_pk_mul_f32 v[54:55], v[54:55], s[12:13] op_sel_hi:[1,0]
	s_or_b64 exec, exec, s[30:31]
	v_mov_b32_e32 v56, v64
	v_mov_b32_e32 v57, v65
	v_mov_b32_e32 v58, v66
	v_mov_b32_e32 v59, v67
	s_and_saveexec_b64 s[24:25], s[46:47]
	s_xor_b64 s[30:31], exec, s[24:25]
	s_cbranch_execz .LBB0_579
	v_cmp_gt_i32_e64 s[56:57], s38, v68
	s_and_saveexec_b64 s[34:35], s[56:57]
	s_cbranch_execz .LBB0_578
	v_add_u32_e32 v60, 0xfffffc00, v125
	v_lshrrev_b32_e32 v61, 4, v68
	v_lshrrev_b32_e32 v60, 6, v60
	v_and_b32_e32 v61, 0xfffff0, v61
	v_add_u32_e32 v60, v60, v61
	v_lshl_or_b32 v60, v60, 8, v72
	v_ashrrev_i32_e32 v61, 31, v60
	v_and_b32_e32 v62, 28, v124
	v_lshlrev_b64 v[60:61], 8, v[60:61]
	v_lshl_add_u64 v[60:61], s[72:73], 0, v[60:61]
	v_lshlrev_b32_e32 v62, 2, v62
	v_mov_b32_e32 v63, v3
	v_lshl_add_u64 v[60:61], v[60:61], 0, v[62:63]
	global_store_dwordx4 v[60:61], v[56:59], off
	s_nop 1

.LBB0_579:
	s_andn2_saveexec_b64 s[30:31], s[30:31]
	v_pk_mul_f32 v[56:57], v[56:57], s[12:13] op_sel_hi:[1,0]
	v_pk_mul_f32 v[58:59], v[58:59], s[12:13] op_sel_hi:[1,0]
	s_or_b64 exec, exec, s[30:31]
	v_cvt_pk_f16_f32 v61, v54, v55
	v_cvt_pk_f16_f32 v60, v52, v53
	v_cvt_pk_f16_f32 v63, v58, v59
	v_cvt_pk_f16_f32 v62, v56, v57
	s_nop 1
	v_permlane32_swap_b32_e32 v60, v62
	v_permlane32_swap_b32_e32 v61, v63
	global_store_dwordx4 v[70:71], v[60:63], off offset:32
	s_nop 1
	s_and_saveexec_b64 s[24:25], s[48:49]
	s_xor_b64 s[30:31], exec, s[24:25]
	s_cbranch_execz .LBB0_585
	v_cmp_gt_i32_e64 s[56:57], s38, v68
	s_and_saveexec_b64 s[34:35], s[56:57]
	s_cbranch_execz .LBB0_584
	v_add_u32_e32 v52, 0xfffffc00, v117
	v_lshrrev_b32_e32 v53, 4, v68
	v_lshrrev_b32_e32 v52, 6, v52
	v_and_b32_e32 v53, 0xfffff0, v53
	v_add_u32_e32 v52, v53, v52
	v_lshl_or_b32 v52, v52, 8, v72
	v_ashrrev_i32_e32 v53, 31, v52
	v_and_b32_e32 v54, 36, v116
	v_lshlrev_b64 v[52:53], 8, v[52:53]
	v_lshl_add_u64 v[52:53], s[72:73], 0, v[52:53]
	v_lshlrev_b32_e32 v54, 2, v54
	v_mov_b32_e32 v55, v3
	v_lshl_add_u64 v[52:53], v[52:53], 0, v[54:55]
	global_store_dwordx4 v[52:53], v[36:39], off
	s_nop 1

.LBB0_585:
	s_andn2_saveexec_b64 s[30:31], s[30:31]
	v_pk_mul_f32 v[36:37], v[36:37], s[12:13] op_sel_hi:[1,0]
	v_pk_mul_f32 v[38:39], v[38:39], s[12:13] op_sel_hi:[1,0]
	s_or_b64 exec, exec, s[30:31]
	s_and_saveexec_b64 s[24:25], s[50:51]
	s_xor_b64 s[30:31], exec, s[24:25]
	s_cbranch_execz .LBB0_591
	v_cmp_gt_i32_e64 s[56:57], s38, v68
	s_and_saveexec_b64 s[34:35], s[56:57]
	s_cbranch_execz .LBB0_590
	v_add_u32_e32 v52, 0xfffffc00, v119
	v_lshrrev_b32_e32 v53, 4, v68
	v_lshrrev_b32_e32 v52, 6, v52
	v_and_b32_e32 v53, 0xfffff0, v53
	v_add_u32_e32 v52, v52, v53
	v_lshl_or_b32 v52, v52, 8, v72
	v_ashrrev_i32_e32 v53, 31, v52
	v_and_b32_e32 v54, 44, v118
	v_lshlrev_b64 v[52:53], 8, v[52:53]
	v_lshl_add_u64 v[52:53], s[72:73], 0, v[52:53]
	v_lshlrev_b32_e32 v54, 2, v54
	v_mov_b32_e32 v55, v3
	v_lshl_add_u64 v[52:53], v[52:53], 0, v[54:55]
	global_store_dwordx4 v[52:53], v[40:43], off
	s_nop 1

.LBB0_591:
	s_andn2_saveexec_b64 s[30:31], s[30:31]
	v_pk_mul_f32 v[40:41], v[40:41], s[12:13] op_sel_hi:[1,0]
	v_pk_mul_f32 v[42:43], v[42:43], s[12:13] op_sel_hi:[1,0]
	s_or_b64 exec, exec, s[30:31]
	v_cvt_pk_f16_f32 v53, v38, v39
	v_cvt_pk_f16_f32 v52, v36, v37
	v_cvt_pk_f16_f32 v55, v42, v43
	v_cvt_pk_f16_f32 v54, v40, v41
	s_nop 1
	v_permlane32_swap_b32_e32 v52, v54
	v_permlane32_swap_b32_e32 v53, v55
	global_store_dwordx4 v[70:71], v[52:55], off offset:64
	s_nop 1
	v_mov_b32_e32 v36, v44
	v_mov_b32_e32 v37, v45
	v_mov_b32_e32 v38, v46
	v_mov_b32_e32 v39, v47
	s_and_saveexec_b64 s[24:25], s[52:53]
	s_xor_b64 s[30:31], exec, s[24:25]
	s_cbranch_execz .LBB0_597
	v_cmp_gt_i32_e64 s[56:57], s38, v68
	s_and_saveexec_b64 s[34:35], s[56:57]
	s_cbranch_execz .LBB0_596
	v_add_u32_e32 v40, 0xfffffc00, v121
	v_lshrrev_b32_e32 v41, 4, v68
	v_lshrrev_b32_e32 v40, 6, v40
	v_and_b32_e32 v41, 0xfffff0, v41
	v_add_u32_e32 v40, v41, v40
	v_lshl_or_b32 v40, v40, 8, v72
	v_ashrrev_i32_e32 v41, 31, v40
	v_and_b32_e32 v42, 52, v120
	v_lshlrev_b64 v[40:41], 8, v[40:41]
	v_lshl_add_u64 v[40:41], s[72:73], 0, v[40:41]
	v_lshlrev_b32_e32 v42, 2, v42
	v_mov_b32_e32 v43, v3
	v_lshl_add_u64 v[40:41], v[40:41], 0, v[42:43]
	global_store_dwordx4 v[40:41], v[36:39], off
	s_nop 1

.LBB0_597:
	s_andn2_saveexec_b64 s[30:31], s[30:31]
	v_pk_mul_f32 v[36:37], v[36:37], s[12:13] op_sel_hi:[1,0]
	v_pk_mul_f32 v[38:39], v[38:39], s[12:13] op_sel_hi:[1,0]
	s_or_b64 exec, exec, s[30:31]
	v_mov_b32_e32 v40, v48
	v_mov_b32_e32 v41, v49
	v_mov_b32_e32 v42, v50
	v_mov_b32_e32 v43, v51
	s_and_saveexec_b64 s[24:25], s[54:55]
	s_xor_b64 s[30:31], exec, s[24:25]
	s_cbranch_execz .LBB0_603
	v_cmp_gt_i32_e64 s[56:57], s38, v68
	s_and_saveexec_b64 s[34:35], s[56:57]
	s_cbranch_execz .LBB0_602
	v_add_u32_e32 v44, 0xfffffc00, v109
	v_lshrrev_b32_e32 v45, 4, v68
	v_lshrrev_b32_e32 v44, 6, v44
	v_and_b32_e32 v45, 0xfffff0, v45
	v_add_u32_e32 v44, v44, v45
	v_lshl_or_b32 v44, v44, 8, v72
	v_ashrrev_i32_e32 v45, 31, v44
	v_and_b32_e32 v46, 60, v108
	v_lshlrev_b64 v[44:45], 8, v[44:45]
	v_lshl_add_u64 v[44:45], s[72:73], 0, v[44:45]
	v_lshlrev_b32_e32 v46, 2, v46
	v_mov_b32_e32 v47, v3
	v_lshl_add_u64 v[44:45], v[44:45], 0, v[46:47]
	global_store_dwordx4 v[44:45], v[40:43], off
	s_nop 1

.LBB0_603:
	s_andn2_saveexec_b64 s[30:31], s[30:31]
	v_pk_mul_f32 v[40:41], v[40:41], s[12:13] op_sel_hi:[1,0]
	v_pk_mul_f32 v[42:43], v[42:43], s[12:13] op_sel_hi:[1,0]
	s_or_b64 exec, exec, s[30:31]
	v_cvt_pk_f16_f32 v45, v38, v39
	v_cvt_pk_f16_f32 v44, v36, v37
	v_cvt_pk_f16_f32 v47, v42, v43
	v_cvt_pk_f16_f32 v46, v40, v41
	s_nop 1
	v_permlane32_swap_b32_e32 v44, v46
	v_permlane32_swap_b32_e32 v45, v47
	global_store_dwordx4 v[70:71], v[44:47], off offset:96
	s_nop 1
	v_or_b32_e32 v36, 0x60, v182
	s_movk_i32 s24, 0xff
	v_bitop3_b32 v38, v182, s24, v211 bitop3:0xc8
	v_add_u32_e32 v36, s83, v36
	s_and_saveexec_b64 s[24:25], vcc
	s_xor_b64 s[30:31], exec, s[24:25]
	s_cbranch_execz .LBB0_609
	v_cmp_gt_i32_e32 vcc, s38, v36
	s_and_saveexec_b64 s[34:35], vcc
	s_cbranch_execz .LBB0_608
	v_add_u32_e32 v37, 0xfffffc00, v138
	v_lshrrev_b32_e32 v39, 4, v36
	v_lshrrev_b32_e32 v37, 6, v37
	v_and_b32_e32 v39, 0xfffff0, v39
	v_add_u32_e32 v37, v39, v37
	v_lshl_or_b32 v40, v37, 8, v38
	v_ashrrev_i32_e32 v41, 31, v40
	v_lshlrev_b64 v[40:41], 8, v[40:41]
	v_lshl_add_u64 v[40:41], s[72:73], 0, v[40:41]
	v_lshlrev_b32_e32 v42, 2, v136
	v_mov_b32_e32 v43, v3
	v_lshl_add_u64 v[40:41], v[40:41], 0, v[42:43]
	global_store_dwordx4 v[40:41], v[20:23], off
	s_nop 1

.LBB0_609:
	s_andn2_saveexec_b64 s[30:31], s[30:31]
	v_pk_mul_f32 v[20:21], v[20:21], s[12:13] op_sel_hi:[1,0]
	v_pk_mul_f32 v[22:23], v[22:23], s[12:13] op_sel_hi:[1,0]
	s_or_b64 exec, exec, s[30:31]
	s_and_saveexec_b64 s[24:25], s[42:43]
	s_xor_b64 s[30:31], exec, s[24:25]
	s_cbranch_execz .LBB0_615
	v_cmp_gt_i32_e32 vcc, s38, v36
	s_and_saveexec_b64 s[34:35], vcc
	s_cbranch_execz .LBB0_614
	v_add_u32_e32 v37, 0xfffffc00, v144
	v_lshrrev_b32_e32 v40, 4, v36
	v_lshrrev_b32_e32 v37, 6, v37
	v_and_b32_e32 v40, 0xfffff0, v40
	v_add_u32_e32 v37, v40, v37
	v_lshl_or_b32 v40, v37, 8, v38
	v_ashrrev_i32_e32 v41, 31, v40
	v_and_b32_e32 v39, 12, v139
	v_lshlrev_b64 v[40:41], 8, v[40:41]
	v_lshl_add_u64 v[40:41], s[72:73], 0, v[40:41]
	v_lshlrev_b32_e32 v42, 2, v39
	v_mov_b32_e32 v43, v3
	v_lshl_add_u64 v[40:41], v[40:41], 0, v[42:43]
	global_store_dwordx4 v[40:41], v[24:27], off
	s_nop 1

.LBB0_615:
	s_andn2_saveexec_b64 s[30:31], s[30:31]
	v_pk_mul_f32 v[24:25], v[24:25], s[12:13] op_sel_hi:[1,0]
	v_pk_mul_f32 v[26:27], v[26:27], s[12:13] op_sel_hi:[1,0]
	s_or_b64 exec, exec, s[30:31]
	v_ashrrev_i32_e32 v37, 31, v36
	v_cvt_pk_f16_f32 v40, v20, v21
	v_lshlrev_b64 v[20:21], 11, v[36:37]
	v_lshl_add_u64 v[20:21], s[28:29], 0, v[20:21]
	v_cvt_pk_f16_f32 v41, v22, v23
	v_cvt_pk_f16_f32 v43, v26, v27
	v_cvt_pk_f16_f32 v42, v24, v25
	v_lshl_add_u64 v[0:1], v[0:1], 1, v[20:21]
	s_nop 0
	v_permlane32_swap_b32_e32 v40, v42
	v_permlane32_swap_b32_e32 v41, v43
	v_lshl_add_u64 v[0:1], v[0:1], 0, v[2:3]
	global_store_dwordx4 v[0:1], v[40:43], off
	s_nop 1
	v_mov_b32_e32 v20, v28
	v_mov_b32_e32 v21, v29
	v_mov_b32_e32 v22, v30
	v_mov_b32_e32 v23, v31
	s_and_saveexec_b64 s[24:25], s[44:45]
	s_xor_b64 s[28:29], exec, s[24:25]
	s_cbranch_execz .LBB0_621
	v_cmp_gt_i32_e32 vcc, s38, v36
	s_and_saveexec_b64 s[30:31], vcc
	s_cbranch_execz .LBB0_620
	v_add_u32_e32 v2, 0xfffffc00, v141
	v_lshrrev_b32_e32 v24, 4, v36
	v_lshrrev_b32_e32 v2, 6, v2
	v_and_b32_e32 v24, 0xfffff0, v24
	v_add_u32_e32 v2, v24, v2
	v_lshl_or_b32 v24, v2, 8, v38
	v_ashrrev_i32_e32 v25, 31, v24
	v_and_b32_e32 v26, 20, v137
	v_lshlrev_b64 v[24:25], 8, v[24:25]
	v_lshl_add_u64 v[24:25], s[72:73], 0, v[24:25]
	v_lshlrev_b32_e32 v26, 2, v26
	v_mov_b32_e32 v27, v3
	v_lshl_add_u64 v[24:25], v[24:25], 0, v[26:27]
	global_store_dwordx4 v[24:25], v[20:23], off
	s_nop 1

.LBB0_621:
	s_andn2_saveexec_b64 s[28:29], s[28:29]
	v_pk_mul_f32 v[20:21], v[20:21], s[12:13] op_sel_hi:[1,0]
	v_pk_mul_f32 v[22:23], v[22:23], s[12:13] op_sel_hi:[1,0]
	s_or_b64 exec, exec, s[28:29]
	v_mov_b32_e32 v24, v32
	v_mov_b32_e32 v25, v33
	v_mov_b32_e32 v26, v34
	v_mov_b32_e32 v27, v35
	s_and_saveexec_b64 s[24:25], s[46:47]
	s_xor_b64 s[28:29], exec, s[24:25]
	s_cbranch_execz .LBB0_627
	v_cmp_gt_i32_e32 vcc, s38, v36
	s_and_saveexec_b64 s[30:31], vcc
	s_cbranch_execz .LBB0_626
	v_add_u32_e32 v2, 0xfffffc00, v125
	v_lshrrev_b32_e32 v28, 4, v36
	v_lshrrev_b32_e32 v2, 6, v2
	v_and_b32_e32 v28, 0xfffff0, v28
	v_add_u32_e32 v2, v2, v28
	v_lshl_or_b32 v28, v2, 8, v38
	v_ashrrev_i32_e32 v29, 31, v28
	v_and_b32_e32 v30, 28, v124
	v_lshlrev_b64 v[28:29], 8, v[28:29]
	v_lshl_add_u64 v[28:29], s[72:73], 0, v[28:29]
	v_lshlrev_b32_e32 v30, 2, v30
	v_mov_b32_e32 v31, v3
	v_lshl_add_u64 v[28:29], v[28:29], 0, v[30:31]
	global_store_dwordx4 v[28:29], v[24:27], off
	s_nop 1

.LBB0_627:
	s_andn2_saveexec_b64 s[28:29], s[28:29]
	v_pk_mul_f32 v[24:25], v[24:25], s[12:13] op_sel_hi:[1,0]
	v_pk_mul_f32 v[26:27], v[26:27], s[12:13] op_sel_hi:[1,0]
	s_or_b64 exec, exec, s[28:29]
	v_cvt_pk_f16_f32 v29, v22, v23
	v_cvt_pk_f16_f32 v28, v20, v21
	v_cvt_pk_f16_f32 v31, v26, v27
	v_cvt_pk_f16_f32 v30, v24, v25
	s_nop 1
	v_permlane32_swap_b32_e32 v28, v30
	v_permlane32_swap_b32_e32 v29, v31
	global_store_dwordx4 v[0:1], v[28:31], off offset:32
	s_nop 1
	s_and_saveexec_b64 s[24:25], s[48:49]
	s_xor_b64 s[28:29], exec, s[24:25]
	s_cbranch_execz .LBB0_633
	v_cmp_gt_i32_e32 vcc, s38, v36
	s_and_saveexec_b64 s[30:31], vcc
	s_cbranch_execz .LBB0_632
	v_add_u32_e32 v2, 0xfffffc00, v117
	v_lshrrev_b32_e32 v20, 4, v36
	v_lshrrev_b32_e32 v2, 6, v2
	v_and_b32_e32 v20, 0xfffff0, v20
	v_add_u32_e32 v2, v20, v2
	v_lshl_or_b32 v20, v2, 8, v38
	v_ashrrev_i32_e32 v21, 31, v20
	v_and_b32_e32 v22, 36, v116
	v_lshlrev_b64 v[20:21], 8, v[20:21]
	v_lshl_add_u64 v[20:21], s[72:73], 0, v[20:21]
	v_lshlrev_b32_e32 v22, 2, v22
	v_mov_b32_e32 v23, v3
	v_lshl_add_u64 v[20:21], v[20:21], 0, v[22:23]
	global_store_dwordx4 v[20:21], v[4:7], off
	s_nop 1

.LBB0_633:
	s_andn2_saveexec_b64 s[28:29], s[28:29]
	v_pk_mul_f32 v[4:5], v[4:5], s[12:13] op_sel_hi:[1,0]
	v_pk_mul_f32 v[6:7], v[6:7], s[12:13] op_sel_hi:[1,0]
	s_or_b64 exec, exec, s[28:29]
	s_and_saveexec_b64 s[24:25], s[50:51]
	s_xor_b64 s[28:29], exec, s[24:25]
	s_cbranch_execz .LBB0_639
	v_cmp_gt_i32_e32 vcc, s38, v36
	s_and_saveexec_b64 s[30:31], vcc
	s_cbranch_execz .LBB0_638
	v_add_u32_e32 v2, 0xfffffc00, v119
	v_lshrrev_b32_e32 v20, 4, v36
	v_lshrrev_b32_e32 v2, 6, v2
	v_and_b32_e32 v20, 0xfffff0, v20
	v_add_u32_e32 v2, v2, v20
	v_lshl_or_b32 v20, v2, 8, v38
	v_ashrrev_i32_e32 v21, 31, v20
	v_and_b32_e32 v22, 44, v118
	v_lshlrev_b64 v[20:21], 8, v[20:21]
	v_lshl_add_u64 v[20:21], s[72:73], 0, v[20:21]
	v_lshlrev_b32_e32 v22, 2, v22
	v_mov_b32_e32 v23, v3
	v_lshl_add_u64 v[20:21], v[20:21], 0, v[22:23]
	global_store_dwordx4 v[20:21], v[8:11], off
	s_nop 1

.LBB0_639:
	s_andn2_saveexec_b64 s[28:29], s[28:29]
	v_pk_mul_f32 v[8:9], v[8:9], s[12:13] op_sel_hi:[1,0]
	v_pk_mul_f32 v[10:11], v[10:11], s[12:13] op_sel_hi:[1,0]
	s_or_b64 exec, exec, s[28:29]
	v_cvt_pk_f16_f32 v21, v6, v7
	v_cvt_pk_f16_f32 v20, v4, v5
	v_cvt_pk_f16_f32 v23, v10, v11
	v_cvt_pk_f16_f32 v22, v8, v9
	s_nop 1
	v_permlane32_swap_b32_e32 v20, v22
	v_permlane32_swap_b32_e32 v21, v23
	global_store_dwordx4 v[0:1], v[20:23], off offset:64
	s_nop 1
	v_mov_b32_e32 v4, v12
	v_mov_b32_e32 v5, v13
	v_mov_b32_e32 v6, v14
	v_mov_b32_e32 v7, v15
	s_and_saveexec_b64 s[24:25], s[52:53]
	s_xor_b64 s[28:29], exec, s[24:25]
	s_cbranch_execz .LBB0_645
	v_cmp_gt_i32_e32 vcc, s38, v36
	s_and_saveexec_b64 s[30:31], vcc
	s_cbranch_execz .LBB0_644
	v_add_u32_e32 v2, 0xfffffc00, v121
	v_lshrrev_b32_e32 v8, 4, v36
	v_lshrrev_b32_e32 v2, 6, v2
	v_and_b32_e32 v8, 0xfffff0, v8
	v_add_u32_e32 v2, v8, v2
	v_lshl_or_b32 v8, v2, 8, v38
	v_ashrrev_i32_e32 v9, 31, v8
	v_and_b32_e32 v10, 52, v120
	v_lshlrev_b64 v[8:9], 8, v[8:9]
	v_lshl_add_u64 v[8:9], s[72:73], 0, v[8:9]
	v_lshlrev_b32_e32 v10, 2, v10
	v_mov_b32_e32 v11, v3
	v_lshl_add_u64 v[8:9], v[8:9], 0, v[10:11]
	global_store_dwordx4 v[8:9], v[4:7], off
	s_nop 1

.LBB0_645:
	s_andn2_saveexec_b64 s[28:29], s[28:29]
	v_pk_mul_f32 v[4:5], v[4:5], s[12:13] op_sel_hi:[1,0]
	v_pk_mul_f32 v[6:7], v[6:7], s[12:13] op_sel_hi:[1,0]
	s_or_b64 exec, exec, s[28:29]
	v_mov_b32_e32 v8, v16
	v_mov_b32_e32 v9, v17
	v_mov_b32_e32 v10, v18
	v_mov_b32_e32 v11, v19
	s_and_saveexec_b64 s[24:25], s[54:55]
	s_xor_b64 s[28:29], exec, s[24:25]
	s_cbranch_execz .LBB0_651
	v_cmp_gt_i32_e32 vcc, s38, v36
	s_and_saveexec_b64 s[30:31], vcc
	s_cbranch_execz .LBB0_650
	v_add_u32_e32 v2, 0xfffffc00, v109
	v_lshrrev_b32_e32 v12, 4, v36
	v_lshrrev_b32_e32 v2, 6, v2
	v_and_b32_e32 v12, 0xfffff0, v12
	v_add_u32_e32 v2, v2, v12
	v_lshl_or_b32 v12, v2, 8, v38
	v_ashrrev_i32_e32 v13, 31, v12
	v_and_b32_e32 v14, 60, v108
	v_lshlrev_b64 v[12:13], 8, v[12:13]
	v_lshl_add_u64 v[12:13], s[72:73], 0, v[12:13]
	v_lshlrev_b32_e32 v14, 2, v14
	v_mov_b32_e32 v15, v3
	v_lshl_add_u64 v[12:13], v[12:13], 0, v[14:15]
	global_store_dwordx4 v[12:13], v[8:11], off
	s_nop 1

.LBB0_1120:
	s_load_dwordx2 s[42:43], s[22:23], 0x90
	s_ashr_i32 s37, s36, 31
	v_lshlrev_b32_e32 v138, 2, v182
	s_lshl_b64 s[44:45], s[36:37], 2
	v_or_b32_e32 v132, v0, v138
	s_waitcnt lgkmcnt(0)
	s_add_u32 s42, s42, s44
	s_addc_u32 s43, s43, s45
	v_ashrrev_i32_e32 v133, 31, v132
	v_lshl_add_u64 v[132:133], v[132:133], 2, s[42:43]
	s_lshl_b64 s[36:37], s[36:37], 1
	v_lshlrev_b32_e32 v2, 4, v182
	v_mov_b32_e32 v139, v3
	s_add_i32 s46, s46, s76
	s_cmp_ge_i32 s46, s59
	s_nop 0
	v_cvt_pk_f16_f32 v134, v116, v117
	v_mov_b32_e32 v116, v118
	v_mov_b32_e32 v117, v119
	s_nop 0
	v_cvt_pk_f16_f32 v135, v116, v117
	v_mov_b32_e32 v116, v120
	v_mov_b32_e32 v117, v121
	s_nop 0
	v_cvt_pk_f16_f32 v136, v116, v117
	v_mov_b32_e32 v116, v122
	v_mov_b32_e32 v117, v123
	v_add_u32_e32 v122, s47, v1
	v_cvt_pk_f16_f32 v137, v116, v117
	v_mov_b64_e32 v[116:117], s[28:29]
	v_mad_i64_i32 v[118:119], s[44:45], v122, s97, v[116:117]
	v_ashrrev_i32_e32 v1, 31, v0
	v_lshl_add_u64 v[120:121], v[118:119], 0, s[36:37]
	v_lshlrev_b64 v[118:119], 1, v[0:1]
	v_lshl_add_u64 v[120:121], v[120:121], 0, v[118:119]
	v_permlane32_swap_b32_e32 v134, v136
	v_permlane32_swap_b32_e32 v135, v137
	v_lshl_add_u64 v[120:121], v[120:121], 0, v[2:3]
	v_lshl_add_u64 v[0:1], v[0:1], 0, v[138:139]
	global_store_dwordx4 v[120:121], v[134:137], off
	s_nop 1
	v_lshl_add_u64 v[0:1], v[0:1], 2, s[42:43]
	v_cvt_pk_f16_f32 v124, v124, v125
	v_cvt_pk_f16_f32 v125, v126, v127
	v_mov_b32_e32 v126, v128
	v_mov_b32_e32 v127, v129
	v_mov_b32_e32 v128, v130
	v_mov_b32_e32 v129, v131
	v_cvt_pk_f16_f32 v126, v126, v127
	v_cvt_pk_f16_f32 v127, v128, v129
	s_nop 0
	v_permlane32_swap_b32_e32 v124, v126
	v_permlane32_swap_b32_e32 v125, v127
	global_store_dwordx4 v[120:121], v[124:127], off offset:32
	s_nop 1
	v_cvt_pk_f16_f32 v100, v100, v101
	v_cvt_pk_f16_f32 v101, v102, v103
	v_mov_b32_e32 v102, v104
	v_mov_b32_e32 v103, v105
	v_mov_b32_e32 v104, v106
	v_mov_b32_e32 v105, v107
	v_cvt_pk_f16_f32 v102, v102, v103
	v_cvt_pk_f16_f32 v103, v104, v105
	s_nop 0
	v_permlane32_swap_b32_e32 v100, v102
	v_permlane32_swap_b32_e32 v101, v103
	global_store_dwordx4 v[120:121], v[100:103], off offset:64
	s_nop 1
	v_mov_b32_e32 v100, v108
	v_mov_b32_e32 v101, v109
	v_mov_b32_e32 v102, v110
	v_mov_b32_e32 v103, v111
	v_cvt_pk_f16_f32 v100, v100, v101
	v_cvt_pk_f16_f32 v101, v102, v103
	v_mov_b32_e32 v102, v112
	v_mov_b32_e32 v103, v113
	v_mov_b32_e32 v104, v114
	v_mov_b32_e32 v105, v115
	v_cvt_pk_f16_f32 v102, v102, v103
	v_cvt_pk_f16_f32 v103, v104, v105
	s_nop 0
	v_permlane32_swap_b32_e32 v100, v102
	v_permlane32_swap_b32_e32 v101, v103
	global_store_dwordx4 v[120:121], v[100:103], off offset:96
	s_nop 1
	s_nop 0
	v_cvt_pk_f16_f32 v100, v84, v85
	v_mov_b32_e32 v84, v86
	v_mov_b32_e32 v85, v87
	s_nop 0
	v_cvt_pk_f16_f32 v101, v84, v85
	v_mov_b32_e32 v84, v88
	v_mov_b32_e32 v85, v89
	s_nop 0
	v_cvt_pk_f16_f32 v102, v84, v85
	v_mov_b32_e32 v84, v90
	v_mov_b32_e32 v85, v91
	s_nop 0
	v_permlane32_swap_b32_e32 v100, v102
	v_cvt_pk_f16_f32 v103, v84, v85
	v_add_u32_e32 v84, 32, v122
	v_mad_i64_i32 v[84:85], s[42:43], v84, s97, v[116:117]
	v_lshl_add_u64 v[84:85], v[84:85], 0, s[36:37]
	v_lshl_add_u64 v[84:85], v[84:85], 0, v[118:119]
	v_permlane32_swap_b32_e32 v101, v103
	v_lshl_add_u64 v[84:85], v[84:85], 0, v[2:3]
	global_store_dwordx4 v[84:85], v[100:103], off
	s_nop 1
	v_mov_b32_e32 v86, v92
	v_mov_b32_e32 v87, v93
	v_mov_b32_e32 v88, v94
	v_mov_b32_e32 v89, v95
	v_cvt_pk_f16_f32 v86, v86, v87
	v_cvt_pk_f16_f32 v87, v88, v89
	v_mov_b32_e32 v88, v96
	v_mov_b32_e32 v89, v97
	v_mov_b32_e32 v90, v98
	v_mov_b32_e32 v91, v99
	v_cvt_pk_f16_f32 v88, v88, v89
	v_cvt_pk_f16_f32 v89, v90, v91
	s_nop 0
	v_permlane32_swap_b32_e32 v86, v88
	v_permlane32_swap_b32_e32 v87, v89
	global_store_dwordx4 v[84:85], v[86:89], off offset:32
	s_nop 1
	v_cvt_pk_f16_f32 v68, v68, v69
	v_cvt_pk_f16_f32 v69, v70, v71
	v_mov_b32_e32 v70, v72
	v_mov_b32_e32 v71, v73
	v_mov_b32_e32 v72, v74
	v_mov_b32_e32 v73, v75
	v_cvt_pk_f16_f32 v70, v70, v71
	v_cvt_pk_f16_f32 v71, v72, v73
	s_nop 0
	v_permlane32_swap_b32_e32 v68, v70
	v_permlane32_swap_b32_e32 v69, v71
	global_store_dwordx4 v[84:85], v[68:71], off offset:64
	s_nop 1
	v_mov_b32_e32 v68, v76
	v_mov_b32_e32 v69, v77
	v_mov_b32_e32 v70, v78
	v_mov_b32_e32 v71, v79
	v_cvt_pk_f16_f32 v68, v68, v69
	v_cvt_pk_f16_f32 v69, v70, v71
	v_mov_b32_e32 v70, v80
	v_mov_b32_e32 v71, v81
	v_mov_b32_e32 v72, v82
	v_mov_b32_e32 v73, v83
	v_cvt_pk_f16_f32 v70, v70, v71
	v_cvt_pk_f16_f32 v71, v72, v73
	s_nop 0
	v_permlane32_swap_b32_e32 v68, v70
	v_permlane32_swap_b32_e32 v69, v71
	global_store_dwordx4 v[84:85], v[68:71], off offset:96
	s_nop 1
	s_nop 0
	v_cvt_pk_f16_f32 v68, v52, v53
	v_mov_b32_e32 v52, v54
	v_mov_b32_e32 v53, v55
	s_nop 0
	v_cvt_pk_f16_f32 v69, v52, v53
	v_mov_b32_e32 v52, v56
	v_mov_b32_e32 v53, v57
	s_nop 0
	v_cvt_pk_f16_f32 v70, v52, v53
	v_mov_b32_e32 v52, v58
	v_mov_b32_e32 v53, v59
	s_nop 0
	v_permlane32_swap_b32_e32 v68, v70
	v_cvt_pk_f16_f32 v71, v52, v53
	v_add_u32_e32 v52, 64, v122
	v_mad_i64_i32 v[52:53], s[42:43], v52, s97, v[116:117]
	v_lshl_add_u64 v[52:53], v[52:53], 0, s[36:37]
	v_lshl_add_u64 v[52:53], v[52:53], 0, v[118:119]
	v_permlane32_swap_b32_e32 v69, v71
	v_lshl_add_u64 v[52:53], v[52:53], 0, v[2:3]
	global_store_dwordx4 v[52:53], v[68:71], off
	s_nop 1
	v_mov_b32_e32 v54, v60
	v_mov_b32_e32 v55, v61
	v_mov_b32_e32 v56, v62
	v_mov_b32_e32 v57, v63
	v_cvt_pk_f16_f32 v54, v54, v55
	v_cvt_pk_f16_f32 v55, v56, v57
	v_mov_b32_e32 v56, v64
	v_mov_b32_e32 v57, v65
	v_mov_b32_e32 v58, v66
	v_mov_b32_e32 v59, v67
	v_cvt_pk_f16_f32 v56, v56, v57
	v_cvt_pk_f16_f32 v57, v58, v59
	s_nop 0
	v_permlane32_swap_b32_e32 v54, v56
	v_permlane32_swap_b32_e32 v55, v57
	global_store_dwordx4 v[52:53], v[54:57], off offset:32
	s_nop 1
	v_cvt_pk_f16_f32 v36, v36, v37
	v_cvt_pk_f16_f32 v37, v38, v39
	v_mov_b32_e32 v38, v40
	v_mov_b32_e32 v39, v41
	v_mov_b32_e32 v40, v42
	v_mov_b32_e32 v41, v43
	v_cvt_pk_f16_f32 v38, v38, v39
	v_cvt_pk_f16_f32 v39, v40, v41
	s_nop 0
	v_permlane32_swap_b32_e32 v36, v38
	v_permlane32_swap_b32_e32 v37, v39
	global_store_dwordx4 v[52:53], v[36:39], off offset:64
	s_nop 1
	v_mov_b32_e32 v36, v44
	v_mov_b32_e32 v37, v45
	v_mov_b32_e32 v38, v46
	v_mov_b32_e32 v39, v47
	v_cvt_pk_f16_f32 v36, v36, v37
	v_cvt_pk_f16_f32 v37, v38, v39
	v_mov_b32_e32 v38, v48
	v_mov_b32_e32 v39, v49
	v_mov_b32_e32 v40, v50
	v_mov_b32_e32 v41, v51
	v_cvt_pk_f16_f32 v38, v38, v39
	v_cvt_pk_f16_f32 v39, v40, v41
	s_nop 0
	v_permlane32_swap_b32_e32 v36, v38
	v_permlane32_swap_b32_e32 v37, v39
	global_store_dwordx4 v[52:53], v[36:39], off offset:96
	s_nop 1
	v_cvt_pk_f16_f32 v20, v20, v21
	v_cvt_pk_f16_f32 v21, v22, v23
	v_mov_b32_e32 v22, v24
	v_mov_b32_e32 v23, v25
	v_mov_b32_e32 v24, v26
	v_mov_b32_e32 v25, v27
	v_cvt_pk_f16_f32 v22, v22, v23
	v_cvt_pk_f16_f32 v23, v24, v25
	v_add_u32_e32 v24, 0x60, v122
	v_mad_i64_i32 v[24:25], s[42:43], v24, s97, v[116:117]
	v_lshl_add_u64 v[24:25], v[24:25], 0, s[36:37]
	v_lshl_add_u64 v[24:25], v[24:25], 0, v[118:119]
	v_permlane32_swap_b32_e32 v20, v22
	v_permlane32_swap_b32_e32 v21, v23
	v_lshl_add_u64 v[26:27], v[24:25], 0, v[2:3]
	global_store_dwordx4 v[26:27], v[20:23], off
	s_nop 1
	v_mov_b32_e32 v20, v28
	v_mov_b32_e32 v21, v29
	v_mov_b32_e32 v22, v30
	v_mov_b32_e32 v23, v31
	v_cvt_pk_f16_f32 v20, v20, v21
	v_cvt_pk_f16_f32 v21, v22, v23
	v_mov_b32_e32 v22, v32
	v_mov_b32_e32 v23, v33
	v_mov_b32_e32 v24, v34
	v_mov_b32_e32 v25, v35
	v_cvt_pk_f16_f32 v22, v22, v23
	v_cvt_pk_f16_f32 v23, v24, v25
	s_nop 0
	v_permlane32_swap_b32_e32 v20, v22
	v_permlane32_swap_b32_e32 v21, v23
	global_store_dwordx4 v[26:27], v[20:23], off offset:32
	s_nop 1
	v_cvt_pk_f16_f32 v4, v4, v5
	v_cvt_pk_f16_f32 v5, v6, v7
	v_mov_b32_e32 v6, v8
	v_mov_b32_e32 v7, v9
	v_mov_b32_e32 v8, v10
	v_mov_b32_e32 v9, v11
	v_cvt_pk_f16_f32 v6, v6, v7
	v_cvt_pk_f16_f32 v7, v8, v9
	s_nop 0
	v_permlane32_swap_b32_e32 v4, v6
	v_permlane32_swap_b32_e32 v5, v7
	global_store_dwordx4 v[26:27], v[4:7], off offset:64
	s_nop 1
	v_mov_b32_e32 v4, v12
	v_mov_b32_e32 v5, v13
	v_mov_b32_e32 v6, v14
	v_mov_b32_e32 v7, v15
	v_cvt_pk_f16_f32 v4, v4, v5
	v_cvt_pk_f16_f32 v5, v6, v7
	v_mov_b32_e32 v0, v16
	v_mov_b32_e32 v1, v17
	s_nop 0
	v_cvt_pk_f16_f32 v6, v0, v1
	v_mov_b32_e32 v0, v18
	v_mov_b32_e32 v1, v19
	s_nop 0
	v_permlane32_swap_b32_e32 v4, v6
	v_cvt_pk_f16_f32 v7, v0, v1
	s_nop 1
	v_permlane32_swap_b32_e32 v5, v7
	global_store_dwordx4 v[26:27], v[4:7], off offset:96
	s_nop 1
	s_cbranch_scc1 .LBB0_1133
.LBB0_1121:
	s_mul_hi_i32 s42, s46, 0x2aaaaaab
	s_lshr_b32 s36, s42, 31
	s_add_i32 s42, s42, s36
	s_lshl_b32 s36, s42, 3
	s_or_b32 s43, s36, s83
	s_and_b64 s[36:37], s[74:75], exec
	v_mov_b32_e32 v0, v200
	s_mul_i32 s37, s42, 6
	s_cselect_b32 s36, s43, s42
	v_ashrrev_i32_e32 v6, 6, v0
	s_sub_i32 s37, s46, s37
	v_bfe_u32 v4, v0, 2, 4
	v_lshlrev_b32_e32 v5, 5, v6
	v_and_b32_e32 v1, 63, v0
	v_or_b32_e32 v7, v5, v4
	s_lshl_b32 s47, s36, 8
	s_lshl_b32 s36, s37, 8
	s_load_dwordx2 s[80:81], s[22:23], 0x90
	s_waitcnt lgkmcnt(0)
	v_bfe_u32 v176, v200, 6, 2
	v_bfe_u32 v177, v200, 5, 1
	v_lshlrev_b32_e32 v176, 6, v176
	v_lshl_or_b32 v176, v177, 2, v176
	v_add_u32_e32 v176, s36, v176
	v_lshlrev_b32_e32 v176, 2, v176
	global_load_dwordx4 v[144:147], v176, s[80:81]
	global_load_dwordx4 v[148:151], v176, s[80:81] offset:32
	global_load_dwordx4 v[152:155], v176, s[80:81] offset:64
	global_load_dwordx4 v[156:159], v176, s[80:81] offset:96
	global_load_dwordx4 v[160:163], v176, s[80:81] offset:128
	global_load_dwordx4 v[164:167], v176, s[80:81] offset:160
	global_load_dwordx4 v[168:171], v176, s[80:81] offset:192
	global_load_dwordx4 v[172:175], v176, s[80:81] offset:224
	v_lshrrev_b32_e32 v2, 4, v0
	v_add_u32_e32 v8, s47, v7
	v_or_b32_e32 v14, 16, v7
	v_add_u32_e32 v12, s36, v7
	v_lshlrev_b32_e32 v7, 4, v1
	v_xor_b32_e32 v2, v2, v0
	v_ashrrev_i32_e32 v9, 31, v8
	v_add_u32_e32 v10, s47, v14
	v_lshl_or_b32 v190, v6, 11, v7
	v_lshlrev_b64 v[8:9], 11, v[8:9]
	v_lshlrev_b32_e32 v2, 4, v2
	v_ashrrev_i32_e32 v11, 31, v10
	v_add_u32_e32 v7, 16, v190
	v_lshl_add_u64 v[8:9], s[26:27], 0, v[8:9]
	v_and_b32_e32 v2, 48, v2
	v_lshlrev_b64 v[10:11], 11, v[10:11]
	v_ashrrev_i32_e32 v13, 31, v12
	v_add_u32_e32 v14, s36, v14
	v_readfirstlane_b32 s37, v7
	v_add_u32_e32 v16, 0x400, v7
	v_lshl_add_u64 v[8:9], v[8:9], 0, v[2:3]
	v_lshl_add_u64 v[10:11], s[26:27], 0, v[10:11]
	v_lshlrev_b64 v[12:13], 11, v[12:13]
	v_ashrrev_i32_e32 v15, 31, v14
	s_mov_b32 m0, s37
	v_readfirstlane_b32 s37, v16
	v_add_u32_e32 v16, 0x4000, v7
	v_lshl_add_u64 v[10:11], v[10:11], 0, v[2:3]
	v_lshl_add_u64 v[12:13], s[24:25], 0, v[12:13]
	v_lshlrev_b64 v[14:15], 11, v[14:15]
	global_load_lds_dwordx4 v[8:9], off
	s_mov_b32 m0, s37
	v_readfirstlane_b32 s37, v16
	v_add_u32_e32 v16, 0x4400, v7
	v_lshl_add_u64 v[12:13], v[12:13], 0, v[2:3]
	v_lshl_add_u64 v[14:15], s[24:25], 0, v[14:15]
	global_load_lds_dwordx4 v[10:11], off
	s_mov_b32 m0, s37
	v_readfirstlane_b32 s37, v16
	v_add_u32_e32 v18, 0x8000, v7
	v_lshl_add_u64 v[14:15], v[14:15], 0, v[2:3]
	global_load_lds_dwordx4 v[12:13], off
	s_mov_b32 m0, s37
	v_readfirstlane_b32 s37, v18
	v_add_u32_e32 v18, 0x8400, v7
	global_load_lds_dwordx4 v[14:15], off
	v_lshl_add_u64 v[16:17], v[8:9], 0, 64
	s_mov_b32 m0, s37
	v_readfirstlane_b32 s37, v18
	v_add_u32_e32 v18, 0xc000, v7
	global_load_lds_dwordx4 v[16:17], off
	v_lshl_add_u64 v[16:17], v[10:11], 0, 64
	s_mov_b32 m0, s37
	v_readfirstlane_b32 s37, v18
	v_add_u32_e32 v7, 0xc400, v7
	global_load_lds_dwordx4 v[16:17], off
	v_lshl_add_u64 v[16:17], v[12:13], 0, 64
	s_mov_b32 m0, s37
	v_readfirstlane_b32 s37, v7
	global_load_lds_dwordx4 v[16:17], off
	s_mov_b32 m0, s37
	s_add_i32 s37, 16, 0x10000
	v_add_u32_e32 v7, s37, v190
	v_lshl_add_u64 v[16:17], v[14:15], 0, 64
	v_readfirstlane_b32 s37, v7
	global_load_lds_dwordx4 v[16:17], off
	v_lshl_add_u64 v[8:9], v[8:9], 0, s[92:93]
	s_mov_b32 m0, s37
	s_nop 0
	global_load_lds_dwordx4 v[8:9], off
	v_lshl_add_u64 v[8:9], v[10:11], 0, s[92:93]
	v_add_u32_e32 v10, 0x400, v7
	s_nop 0
	v_readfirstlane_b32 s37, v10
	v_add_u32_e32 v10, 0x4000, v7
	s_mov_b32 m0, s37
	v_readfirstlane_b32 s37, v10
	v_add_u32_e32 v7, 0x4400, v7
	global_load_lds_dwordx4 v[8:9], off
	v_lshl_add_u64 v[8:9], v[12:13], 0, s[92:93]
	s_mov_b32 m0, s37
	v_readfirstlane_b32 s37, v7
	global_load_lds_dwordx4 v[8:9], off
	v_lshl_add_u64 v[8:9], v[14:15], 0, s[92:93]
	s_mov_b32 m0, s37
	v_readfirstlane_b32 s37, v0
	global_load_lds_dwordx4 v[8:9], off
	s_waitcnt vmcnt(8)
	s_and_b32 s43, s37, 0xffffff00
	s_cmpk_lg_i32 s43, 0x100
	s_barrier
	s_cbranch_scc1 .LBB0_1123
	s_barrier
.LBB0_1123:
	v_lshrrev_b32_e32 v7, 30, v6
	v_add_u32_e32 v7, v6, v7
	v_ashrrev_i32_e32 v7, 2, v7
	v_mul_i32_i24_e32 v8, 4, v7
	v_sub_u32_e32 v6, v6, v8
	v_and_b32_e32 v8, 31, v0
	v_lshrrev_b32_e32 v9, 2, v0
	v_bfe_u32 v10, v0, 2, 2
	v_lshlrev_b32_e32 v0, 6, v6
	v_lshrrev_b32_e32 v182, 5, v1
	v_or_b32_e32 v6, v0, v8
	v_lshlrev_b32_e32 v192, 6, v6
	v_bitop3_b32 v6, v182, v9, 3 bitop3:0x78
	v_lshl_or_b32 v1, v7, 7, v8
	v_lshlrev_b32_e32 v193, 4, v6
	v_bitop3_b32 v6, v182, v10, 2 bitop3:0x36
	v_or_b32_e32 v8, 16, v4
	s_lshl_b32 s43, s46, 8
	v_lshlrev_b32_e32 v194, 4, v6
	v_or_b32_e32 v6, s43, v8
	v_add_u32_e32 v6, v6, v5
	s_mulk_i32 s42, 0x600
	v_subrev_u32_e32 v6, s42, v6
	v_ashrrev_i32_e32 v7, 31, v6
	v_lshlrev_b64 v[6:7], 11, v[6:7]
	v_or_b32_e32 v6, v6, v2
	v_lshl_add_u64 v[180:181], s[30:31], 0, v[6:7]
	v_or_b32_e32 v6, s43, v4
	v_add_u32_e32 v6, v6, v5
	v_subrev_u32_e32 v6, s42, v6
	v_ashrrev_i32_e32 v7, 31, v6
	v_lshlrev_b64 v[6:7], 11, v[6:7]
	v_or_b32_e32 v6, v6, v2
	v_lshl_add_u64 v[184:185], s[30:31], 0, v[6:7]
	v_add3_u32 v6, v8, s47, v5
	v_add3_u32 v4, v4, s47, v5
	v_ashrrev_i32_e32 v7, 31, v6
	v_ashrrev_i32_e32 v5, 31, v4
	v_lshlrev_b64 v[6:7], 11, v[6:7]
	v_lshlrev_b64 v[4:5], 11, v[4:5]
	v_or_b32_e32 v6, v6, v2
	v_or_b32_e32 v4, v4, v2
	v_mov_b32_e32 v116, v144
	v_lshlrev_b32_e32 v191, 6, v1
	v_lshl_add_u64 v[186:187], s[34:35], 0, v[6:7]
	v_lshl_add_u64 v[188:189], s[34:35], 0, v[4:5]
	s_mov_b32 s48, 0x18000
	s_mov_b32 s49, 0
	s_mov_b64 s[42:43], 0
	s_mov_b32 s50, 0
	v_mov_b32_e32 v117, v145
	v_mov_b32_e32 v118, v146
	v_mov_b32_e32 v119, v147
	v_mov_b32_e32 v120, v148
	v_mov_b32_e32 v121, v149
	v_mov_b32_e32 v122, v150
	v_mov_b32_e32 v123, v151
	v_mov_b32_e32 v124, v152
	v_mov_b32_e32 v125, v153
	v_mov_b32_e32 v126, v154
	v_mov_b32_e32 v127, v155
	v_mov_b32_e32 v128, v156
	v_mov_b32_e32 v129, v157
	v_mov_b32_e32 v130, v158
	v_mov_b32_e32 v131, v159
	v_mov_b32_e32 v100, v160
	v_mov_b32_e32 v101, v161
	v_mov_b32_e32 v102, v162
	v_mov_b32_e32 v103, v163
	v_mov_b32_e32 v104, v164
	v_mov_b32_e32 v105, v165
	v_mov_b32_e32 v106, v166
	v_mov_b32_e32 v107, v167
	v_mov_b32_e32 v108, v168
	v_mov_b32_e32 v109, v169
	v_mov_b32_e32 v110, v170
	v_mov_b32_e32 v111, v171
	v_mov_b32_e32 v112, v172
	v_mov_b32_e32 v113, v173
	v_mov_b32_e32 v114, v174
	v_mov_b32_e32 v115, v175
	v_mov_b32_e32 v84, v144
	v_mov_b32_e32 v85, v145
	v_mov_b32_e32 v86, v146
	v_mov_b32_e32 v87, v147
	v_mov_b32_e32 v88, v148
	v_mov_b32_e32 v89, v149
	v_mov_b32_e32 v90, v150
	v_mov_b32_e32 v91, v151
	v_mov_b32_e32 v92, v152
	v_mov_b32_e32 v93, v153
	v_mov_b32_e32 v94, v154
	v_mov_b32_e32 v95, v155
	v_mov_b32_e32 v96, v156
	v_mov_b32_e32 v97, v157
	v_mov_b32_e32 v98, v158
	v_mov_b32_e32 v99, v159
	v_mov_b32_e32 v68, v160
	v_mov_b32_e32 v69, v161
	v_mov_b32_e32 v70, v162
	v_mov_b32_e32 v71, v163
	v_mov_b32_e32 v72, v164
	v_mov_b32_e32 v73, v165
	v_mov_b32_e32 v74, v166
	v_mov_b32_e32 v75, v167
	v_mov_b32_e32 v76, v168
	v_mov_b32_e32 v77, v169
	v_mov_b32_e32 v78, v170
	v_mov_b32_e32 v79, v171
	v_mov_b32_e32 v80, v172
	v_mov_b32_e32 v81, v173
	v_mov_b32_e32 v82, v174
	v_mov_b32_e32 v83, v175
	v_mov_b32_e32 v52, v144
	v_mov_b32_e32 v53, v145
	v_mov_b32_e32 v54, v146
	v_mov_b32_e32 v55, v147
	v_mov_b32_e32 v56, v148
	v_mov_b32_e32 v57, v149
	v_mov_b32_e32 v58, v150
	v_mov_b32_e32 v59, v151
	v_mov_b32_e32 v60, v152
	v_mov_b32_e32 v61, v153
	v_mov_b32_e32 v62, v154
	v_mov_b32_e32 v63, v155
	v_mov_b32_e32 v64, v156
	v_mov_b32_e32 v65, v157
	v_mov_b32_e32 v66, v158
	v_mov_b32_e32 v67, v159
	v_mov_b32_e32 v36, v160
	v_mov_b32_e32 v37, v161
	v_mov_b32_e32 v38, v162
	v_mov_b32_e32 v39, v163
	v_mov_b32_e32 v40, v164
	v_mov_b32_e32 v41, v165
	v_mov_b32_e32 v42, v166
	v_mov_b32_e32 v43, v167
	v_mov_b32_e32 v44, v168
	v_mov_b32_e32 v45, v169
	v_mov_b32_e32 v46, v170
	v_mov_b32_e32 v47, v171
	v_mov_b32_e32 v48, v172
	v_mov_b32_e32 v49, v173
	v_mov_b32_e32 v50, v174
	v_mov_b32_e32 v51, v175
	v_mov_b32_e32 v20, v144
	v_mov_b32_e32 v21, v145
	v_mov_b32_e32 v22, v146
	v_mov_b32_e32 v23, v147
	v_mov_b32_e32 v24, v148
	v_mov_b32_e32 v25, v149
	v_mov_b32_e32 v26, v150
	v_mov_b32_e32 v27, v151
	v_mov_b32_e32 v28, v152
	v_mov_b32_e32 v29, v153
	v_mov_b32_e32 v30, v154
	v_mov_b32_e32 v31, v155
	v_mov_b32_e32 v32, v156
	v_mov_b32_e32 v33, v157
	v_mov_b32_e32 v34, v158
	v_mov_b32_e32 v35, v159
	v_mov_b32_e32 v4, v160
	v_mov_b32_e32 v5, v161
	v_mov_b32_e32 v6, v162
	v_mov_b32_e32 v7, v163
	v_mov_b32_e32 v8, v164
	v_mov_b32_e32 v9, v165
	v_mov_b32_e32 v10, v166
	v_mov_b32_e32 v11, v167
	v_mov_b32_e32 v12, v168
	v_mov_b32_e32 v13, v169
	v_mov_b32_e32 v14, v170
	v_mov_b32_e32 v15, v171
	v_mov_b32_e32 v16, v172
	v_mov_b32_e32 v17, v173
	v_mov_b32_e32 v18, v174
	v_mov_b32_e32 v19, v175
	s_branch .LBB0_1125
